# P3 gates stored lane-linear (1 KiB per wave-instruction) + hand-scheduled rescale hook with 4-deep gate loads, on top of attention edits
# speedup vs baseline: 1.0193x; 1.0057x over previous
.LBB0_587:
	s_lshl_b32 s14, s14, 5
	s_and_b32 s26, s14, 0x60
	s_mov_b64 s[14:15], 0x80
	s_add_i32 m0, s69, 0x18000
	v_lshl_add_u64 v[8:9], v[8:9], 0, s[14:15]
	s_lshl_b32 s21, s19, 13
	s_lshl_b32 s24, s26, 7
	s_waitcnt vmcnt(2)
	s_barrier
	global_load_lds_dwordx4 v[8:9], off
	v_lshl_add_u64 v[6:7], v[6:7], 0, s[14:15]
	s_add_i32 m0, s69, 0x1a000
	s_add_i32 s73, s69, 0x8000
	s_add_i32 s76, s69, 0xa000
	global_load_lds_dwordx4 v[6:7], off
	v_lshl_add_u64 v[2:3], v[2:3], 0, s[14:15]
	s_mov_b32 m0, s73
	s_add_u32 s22, s60, 0xa0080
	global_load_lds_dwordx4 v[2:3], off
	v_lshl_add_u64 v[2:3], v[4:5], 0, s[14:15]
	s_mov_b32 m0, s76
	s_addc_u32 s23, s61, 0
	global_load_lds_dwordx4 v[2:3], off
	s_add_i32 m0, s69, 0x1c000
	v_lshl_add_u64 v[2:3], s[22:23], 0, v[148:149]
	global_load_lds_dwordx4 v[2:3], off
	v_lshl_add_u64 v[2:3], s[22:23], 0, v[144:145]
	s_add_i32 m0, s69, 0x1e000
	s_mov_b64 s[22:23], 0xa0080
	global_load_lds_dwordx4 v[2:3], off
	v_lshrrev_b32_e32 v2, 1, v10
	v_and_b32_e32 v2, 24, v2
	v_and_b32_e32 v3, 15, v10
	v_lshlrev_b32_e32 v4, 1, v2
	v_lshl_or_b32 v172, s19, 6, v3
	v_lshl_or_b32 v3, v3, 6, v4
	v_lshlrev_b32_e32 v4, 2, v10
	v_and_b32_e32 v4, 32, v4
	v_bitop3_b32 v6, v3, s21, v4 bitop3:0xde
	v_bitop3_b32 v173, v3, s24, v4 bitop3:0xde
	s_mov_b32 s21, 0xa000
	v_lshrrev_b32_e32 v3, 1, v15
	v_mul_lo_u32 v4, v14, s20
	v_mad_u64_u32 v[4:5], s[24:25], v3, s21, v[4:5]
	v_or_b32_e32 v3, v4, v16
	v_add_lshl_u32 v4, v3, v17, 1
	v_mov_b32_e32 v5, v0
	v_lshl_add_u64 v[152:153], v[4:5], 0, s[22:23]
	v_lshrrev_b32_e32 v1, 1, v1
	v_mul_lo_u32 v4, v11, s20
	v_mad_u64_u32 v[4:5], s[20:21], v1, s21, v[4:5]
	s_waitcnt vmcnt(6)
	v_or_b32_e32 v1, v4, v12
	s_cmpk_lt_u32 s18, 0x100
	v_add_lshl_u32 v4, v1, v13, 1
	v_mov_b32_e32 v5, v0
	v_lshlrev_b32_e32 v158, 1, v2
	s_cselect_b64 s[18:19], -1, 0
	v_lshl_add_u64 v[154:155], v[4:5], 0, s[22:23]
	s_movk_i32 s77, 0x3000
	v_mov_b64_e32 v[156:157], s[6:7]
	s_lshl_b32 s6, s26, 1
	v_mov_b32_e32 v160, v158
	v_mov_b32_e32 v161, v0
	s_movk_i32 s78, 0x1000
	s_mov_b64 s[20:21], 0x800
	s_mov_b64 s[22:23], 0x800
	s_add_i32 s79, 0, 0x10000
	s_add_i32 s80, 0, 0x14000
	v_add_u32_e32 v174, 0, v6
	s_mov_b64 s[24:25], 0
	s_mov_b64 s[26:27], 0x800
	s_mov_b64 s[46:47], 0x10000
	s_mov_b64 s[48:49], 0x50000
	s_mov_b32 s81, 0xc2700000
	v_mov_b32_e32 v176, 0x42700000
	s_mov_b32 s87, 0
	s_mov_b32 s84, 0
	s_mov_b64 s[50:51], s[58:59]
	s_mov_b64 s[52:53], s[60:61]
	s_barrier
	s_branch .LBB0_590

.LBB0_596:
	s_lshl_b32 s98, s56, 3
	s_add_i32 s98, s98, s2
	s_mul_i32 s98, s98, 3
	v_lshl_add_u32 v164, s56, 8, v172
	s_cmp_eq_u32 s87, 3
	v_mad_i64_i32 v[162:163], s[56:57], v164, s77, v[156:157]
	s_cselect_b64 s[62:63], -1, 0
	s_lshl_b32 s56, s2, 8
	s_ashr_i32 s57, s56, 31
	v_lshl_add_u64 v[2:3], s[56:57], 1, v[162:163]
	s_mov_b32 s7, s3
	v_lshl_add_u64 v[2:3], v[2:3], 0, s[6:7]
	v_lshl_add_u64 v[166:167], v[2:3], 0, v[160:161]
	s_add_i32 s7, s88, -2
	v_mov_b32_e32 v2, v0
	v_mov_b32_e32 v3, v0
	s_add_u32 s89, s60, 0x100
	v_mov_b32_e32 v1, v0
	v_mov_b64_e32 v[6:7], v[2:3]
	v_mov_b64_e32 v[10:11], v[2:3]
	v_mov_b64_e32 v[22:23], v[2:3]
	v_mov_b64_e32 v[26:27], v[2:3]
	v_mov_b64_e32 v[38:39], v[2:3]
	v_mov_b64_e32 v[42:43], v[2:3]
	v_mov_b64_e32 v[54:55], v[2:3]
	v_mov_b64_e32 v[58:59], v[2:3]
	v_mov_b64_e32 v[14:15], v[2:3]
	v_mov_b64_e32 v[18:19], v[2:3]
	v_mov_b64_e32 v[30:31], v[2:3]
	v_mov_b64_e32 v[34:35], v[2:3]
	v_mov_b64_e32 v[46:47], v[2:3]
	v_mov_b64_e32 v[50:51], v[2:3]
	v_mov_b64_e32 v[62:63], v[2:3]
	v_mov_b64_e32 v[66:67], v[2:3]
	v_mov_b64_e32 v[70:71], v[2:3]
	v_mov_b64_e32 v[74:75], v[2:3]
	v_mov_b64_e32 v[86:87], v[2:3]
	v_mov_b64_e32 v[90:91], v[2:3]
	v_mov_b64_e32 v[102:103], v[2:3]
	v_mov_b64_e32 v[106:107], v[2:3]
	v_mov_b64_e32 v[118:119], v[2:3]
	v_mov_b64_e32 v[122:123], v[2:3]
	v_mov_b64_e32 v[78:79], v[2:3]
	v_mov_b64_e32 v[82:83], v[2:3]
	v_mov_b64_e32 v[94:95], v[2:3]
	v_mov_b64_e32 v[98:99], v[2:3]
	v_mov_b64_e32 v[110:111], v[2:3]
	v_mov_b64_e32 v[114:115], v[2:3]
	v_mov_b64_e32 v[126:127], v[2:3]
	v_mov_b64_e32 v[130:131], v[2:3]
	v_ashrrev_i32_e32 v165, 31, v164
	s_addc_u32 s90, s61, 0
	v_lshl_add_u64 v[168:169], s[58:59], 0, v[152:153]
	v_lshl_add_u64 v[170:171], s[58:59], 0, v[154:155]
	s_mov_b32 s64, 0
	s_mov_b64 s[60:61], 0
	s_xor_b64 s[62:63], s[62:63], -1
	v_mov_b64_e32 v[4:5], v[0:1]
	v_mov_b64_e32 v[8:9], v[0:1]
	v_mov_b64_e32 v[20:21], v[0:1]
	v_mov_b64_e32 v[24:25], v[0:1]
	v_mov_b64_e32 v[36:37], v[0:1]
	v_mov_b64_e32 v[40:41], v[0:1]
	v_mov_b64_e32 v[52:53], v[0:1]
	v_mov_b64_e32 v[56:57], v[0:1]
	v_mov_b64_e32 v[12:13], v[0:1]
	v_mov_b64_e32 v[16:17], v[0:1]
	v_mov_b64_e32 v[28:29], v[0:1]
	v_mov_b64_e32 v[32:33], v[0:1]
	v_mov_b64_e32 v[44:45], v[0:1]
	v_mov_b64_e32 v[48:49], v[0:1]
	v_mov_b64_e32 v[60:61], v[0:1]
	v_mov_b64_e32 v[64:65], v[0:1]
	v_mov_b64_e32 v[68:69], v[0:1]
	v_mov_b64_e32 v[72:73], v[0:1]
	v_mov_b64_e32 v[84:85], v[0:1]
	v_mov_b64_e32 v[88:89], v[0:1]
	v_mov_b64_e32 v[100:101], v[0:1]
	v_mov_b64_e32 v[104:105], v[0:1]
	v_mov_b64_e32 v[116:117], v[0:1]
	v_mov_b64_e32 v[120:121], v[0:1]
	v_mov_b64_e32 v[76:77], v[0:1]
	v_mov_b64_e32 v[80:81], v[0:1]
	v_mov_b64_e32 v[92:93], v[0:1]
	v_mov_b64_e32 v[96:97], v[0:1]
	v_mov_b64_e32 v[108:109], v[0:1]
	v_mov_b64_e32 v[112:113], v[0:1]
	v_mov_b64_e32 v[124:125], v[0:1]
	v_mov_b64_e32 v[128:129], v[0:1]
.LBB0_597:
	s_and_b32 s2, s64, 0x7ffffff6
	s_cmp_lg_u32 s2, 16
	s_cselect_b64 s[66:67], -1, 0
	s_or_b64 s[66:67], s[62:63], s[66:67]
	s_and_b64 vcc, exec, s[66:67]
	s_cbranch_vccnz .LBB0_599
	s_cmp_eq_u32 s64, 16
	s_cselect_b32 s99, 0, 1
	s_add_i32 s99, s98, s99
	s_lshl_b32 s99, s99, 17
	s_add_u32 s100, s38, 0xba00000
	s_addc_u32 s101, s39, 0
	s_add_u32 s100, s100, s99
	s_addc_u32 s101, s101, 0
	v_lshrrev_b32_e32 v2, 6, v175
	v_mul_u32_u24_e32 v2, 0x3c00, v2
	v_lshl_add_u32 v2, v175, 4, v2
	v_mov_b32_e32 v3, 0
	v_lshl_add_u64 v[2:3], s[100:101], 0, v[2:3]
	s_mov_b64 s[100:101], 0x20000
	v_lshl_add_u64 v[254:255], v[2:3], 0, s[100:101]
	global_load_dwordx4 v[132:135], v[2:3], off
	global_load_dwordx4 v[136:139], v[2:3], off offset:1024
	global_load_dwordx4 v[140:143], v[254:255], off
	global_load_dwordx4 v[188:191], v[254:255], off offset:1024
	v_lshl_add_u64 v[2:3], v[2:3], 0, s[20:21]
	v_lshl_add_u64 v[254:255], v[254:255], 0, s[20:21]
	global_load_dwordx4 v[192:195], v[2:3], off
	global_load_dwordx4 v[196:199], v[2:3], off offset:1024
	global_load_dwordx4 v[200:203], v[254:255], off
	global_load_dwordx4 v[204:207], v[254:255], off offset:1024
	v_lshl_add_u64 v[2:3], v[2:3], 0, s[20:21]
	v_lshl_add_u64 v[254:255], v[254:255], 0, s[20:21]
	global_load_dwordx4 v[208:211], v[2:3], off
	global_load_dwordx4 v[212:215], v[2:3], off offset:1024
	global_load_dwordx4 v[216:219], v[254:255], off
	global_load_dwordx4 v[220:223], v[254:255], off offset:1024
	v_lshl_add_u64 v[2:3], v[2:3], 0, s[20:21]
	v_lshl_add_u64 v[254:255], v[254:255], 0, s[20:21]
	global_load_dwordx4 v[224:227], v[2:3], off
	global_load_dwordx4 v[228:231], v[2:3], off offset:1024
	global_load_dwordx4 v[232:235], v[254:255], off
	global_load_dwordx4 v[236:239], v[254:255], off offset:1024
	v_lshl_add_u64 v[2:3], v[2:3], 0, s[20:21]
	v_lshl_add_u64 v[254:255], v[254:255], 0, s[20:21]
	s_waitcnt vmcnt(12)
	v_lshlrev_b32_e32 v178, 16, v140
	v_and_b32_e32 v179, 0xffff0000, v140
	v_lshlrev_b32_e32 v180, 16, v141
	v_and_b32_e32 v181, 0xffff0000, v141
	v_lshlrev_b32_e32 v182, 16, v142
	v_and_b32_e32 v183, 0xffff0000, v142
	v_lshlrev_b32_e32 v184, 16, v143
	v_and_b32_e32 v185, 0xffff0000, v143
	v_rcp_f32_e32 v178, v178
	v_rcp_f32_e32 v179, v179
	v_rcp_f32_e32 v180, v180
	v_rcp_f32_e32 v181, v181
	v_rcp_f32_e32 v182, v182
	v_rcp_f32_e32 v183, v183
	v_rcp_f32_e32 v184, v184
	v_rcp_f32_e32 v185, v185
	v_lshlrev_b32_e32 v140, 16, v132
	v_and_b32_e32 v141, 0xffff0000, v132
	v_lshlrev_b32_e32 v142, 16, v133
	v_and_b32_e32 v143, 0xffff0000, v133
	v_lshlrev_b32_e32 v132, 16, v134
	v_and_b32_e32 v133, 0xffff0000, v134
	v_lshlrev_b32_e32 v134, 16, v135
	v_and_b32_e32 v135, 0xffff0000, v135
	v_pk_mul_f32 v[178:179], v[178:179], v[140:141]
	v_pk_mul_f32 v[180:181], v[180:181], v[142:143]
	v_pk_mul_f32 v[182:183], v[182:183], v[132:133]
	v_pk_mul_f32 v[184:185], v[184:185], v[134:135]
	v_pk_mul_f32 v[128:129], v[128:129], v[178:179]
	v_pk_mul_f32 v[130:131], v[130:131], v[180:181]
	v_pk_mul_f32 v[124:125], v[124:125], v[182:183]
	v_pk_mul_f32 v[126:127], v[126:127], v[184:185]
	v_lshlrev_b32_e32 v246, 16, v188
	v_and_b32_e32 v247, 0xffff0000, v188
	v_lshlrev_b32_e32 v248, 16, v189
	v_and_b32_e32 v249, 0xffff0000, v189
	v_lshlrev_b32_e32 v250, 16, v190
	v_and_b32_e32 v251, 0xffff0000, v190
	v_lshlrev_b32_e32 v252, 16, v191
	v_and_b32_e32 v253, 0xffff0000, v191
	v_rcp_f32_e32 v246, v246
	v_rcp_f32_e32 v247, v247
	v_rcp_f32_e32 v248, v248
	v_rcp_f32_e32 v249, v249
	v_rcp_f32_e32 v250, v250
	v_rcp_f32_e32 v251, v251
	v_rcp_f32_e32 v252, v252
	v_rcp_f32_e32 v253, v253
	v_lshlrev_b32_e32 v188, 16, v136
	v_and_b32_e32 v189, 0xffff0000, v136
	v_lshlrev_b32_e32 v190, 16, v137
	v_and_b32_e32 v191, 0xffff0000, v137
	v_lshlrev_b32_e32 v136, 16, v138
	v_and_b32_e32 v137, 0xffff0000, v138
	v_lshlrev_b32_e32 v138, 16, v139
	v_and_b32_e32 v139, 0xffff0000, v139
	v_pk_mul_f32 v[246:247], v[246:247], v[188:189]
	v_pk_mul_f32 v[248:249], v[248:249], v[190:191]
	v_pk_mul_f32 v[250:251], v[250:251], v[136:137]
	v_pk_mul_f32 v[252:253], v[252:253], v[138:139]
	v_pk_mul_f32 v[120:121], v[120:121], v[246:247]
	v_pk_mul_f32 v[122:123], v[122:123], v[248:249]
	v_pk_mul_f32 v[116:117], v[116:117], v[250:251]
	v_pk_mul_f32 v[118:119], v[118:119], v[252:253]
	global_load_dwordx4 v[132:135], v[2:3], off
	global_load_dwordx4 v[136:139], v[2:3], off offset:1024
	global_load_dwordx4 v[140:143], v[254:255], off
	global_load_dwordx4 v[188:191], v[254:255], off offset:1024
	v_lshl_add_u64 v[2:3], v[2:3], 0, s[20:21]
	v_lshl_add_u64 v[254:255], v[254:255], 0, s[20:21]
	s_waitcnt vmcnt(12)
	v_lshlrev_b32_e32 v178, 16, v200
	v_and_b32_e32 v179, 0xffff0000, v200
	v_lshlrev_b32_e32 v180, 16, v201
	v_and_b32_e32 v181, 0xffff0000, v201
	v_lshlrev_b32_e32 v182, 16, v202
	v_and_b32_e32 v183, 0xffff0000, v202
	v_lshlrev_b32_e32 v184, 16, v203
	v_and_b32_e32 v185, 0xffff0000, v203
	v_rcp_f32_e32 v178, v178
	v_rcp_f32_e32 v179, v179
	v_rcp_f32_e32 v180, v180
	v_rcp_f32_e32 v181, v181
	v_rcp_f32_e32 v182, v182
	v_rcp_f32_e32 v183, v183
	v_rcp_f32_e32 v184, v184
	v_rcp_f32_e32 v185, v185
	v_lshlrev_b32_e32 v200, 16, v192
	v_and_b32_e32 v201, 0xffff0000, v192
	v_lshlrev_b32_e32 v202, 16, v193
	v_and_b32_e32 v203, 0xffff0000, v193
	v_lshlrev_b32_e32 v192, 16, v194
	v_and_b32_e32 v193, 0xffff0000, v194
	v_lshlrev_b32_e32 v194, 16, v195
	v_and_b32_e32 v195, 0xffff0000, v195
	v_pk_mul_f32 v[178:179], v[178:179], v[200:201]
	v_pk_mul_f32 v[180:181], v[180:181], v[202:203]
	v_pk_mul_f32 v[182:183], v[182:183], v[192:193]
	v_pk_mul_f32 v[184:185], v[184:185], v[194:195]
	v_pk_mul_f32 v[112:113], v[112:113], v[178:179]
	v_pk_mul_f32 v[114:115], v[114:115], v[180:181]
	v_pk_mul_f32 v[108:109], v[108:109], v[182:183]
	v_pk_mul_f32 v[110:111], v[110:111], v[184:185]
	v_lshlrev_b32_e32 v246, 16, v204
	v_and_b32_e32 v247, 0xffff0000, v204
	v_lshlrev_b32_e32 v248, 16, v205
	v_and_b32_e32 v249, 0xffff0000, v205
	v_lshlrev_b32_e32 v250, 16, v206
	v_and_b32_e32 v251, 0xffff0000, v206
	v_lshlrev_b32_e32 v252, 16, v207
	v_and_b32_e32 v253, 0xffff0000, v207
	v_rcp_f32_e32 v246, v246
	v_rcp_f32_e32 v247, v247
	v_rcp_f32_e32 v248, v248
	v_rcp_f32_e32 v249, v249
	v_rcp_f32_e32 v250, v250
	v_rcp_f32_e32 v251, v251
	v_rcp_f32_e32 v252, v252
	v_rcp_f32_e32 v253, v253
	v_lshlrev_b32_e32 v204, 16, v196
	v_and_b32_e32 v205, 0xffff0000, v196
	v_lshlrev_b32_e32 v206, 16, v197
	v_and_b32_e32 v207, 0xffff0000, v197
	v_lshlrev_b32_e32 v196, 16, v198
	v_and_b32_e32 v197, 0xffff0000, v198
	v_lshlrev_b32_e32 v198, 16, v199
	v_and_b32_e32 v199, 0xffff0000, v199
	v_pk_mul_f32 v[246:247], v[246:247], v[204:205]
	v_pk_mul_f32 v[248:249], v[248:249], v[206:207]
	v_pk_mul_f32 v[250:251], v[250:251], v[196:197]
	v_pk_mul_f32 v[252:253], v[252:253], v[198:199]
	v_pk_mul_f32 v[104:105], v[104:105], v[246:247]
	v_pk_mul_f32 v[106:107], v[106:107], v[248:249]
	v_pk_mul_f32 v[100:101], v[100:101], v[250:251]
	v_pk_mul_f32 v[102:103], v[102:103], v[252:253]
	global_load_dwordx4 v[192:195], v[2:3], off
	global_load_dwordx4 v[196:199], v[2:3], off offset:1024
	global_load_dwordx4 v[200:203], v[254:255], off
	global_load_dwordx4 v[204:207], v[254:255], off offset:1024
	v_lshl_add_u64 v[2:3], v[2:3], 0, s[20:21]
	v_lshl_add_u64 v[254:255], v[254:255], 0, s[20:21]
	s_waitcnt vmcnt(12)
	v_lshlrev_b32_e32 v178, 16, v216
	v_and_b32_e32 v179, 0xffff0000, v216
	v_lshlrev_b32_e32 v180, 16, v217
	v_and_b32_e32 v181, 0xffff0000, v217
	v_lshlrev_b32_e32 v182, 16, v218
	v_and_b32_e32 v183, 0xffff0000, v218
	v_lshlrev_b32_e32 v184, 16, v219
	v_and_b32_e32 v185, 0xffff0000, v219
	v_rcp_f32_e32 v178, v178
	v_rcp_f32_e32 v179, v179
	v_rcp_f32_e32 v180, v180
	v_rcp_f32_e32 v181, v181
	v_rcp_f32_e32 v182, v182
	v_rcp_f32_e32 v183, v183
	v_rcp_f32_e32 v184, v184
	v_rcp_f32_e32 v185, v185
	v_lshlrev_b32_e32 v216, 16, v208
	v_and_b32_e32 v217, 0xffff0000, v208
	v_lshlrev_b32_e32 v218, 16, v209
	v_and_b32_e32 v219, 0xffff0000, v209
	v_lshlrev_b32_e32 v208, 16, v210
	v_and_b32_e32 v209, 0xffff0000, v210
	v_lshlrev_b32_e32 v210, 16, v211
	v_and_b32_e32 v211, 0xffff0000, v211
	v_pk_mul_f32 v[178:179], v[178:179], v[216:217]
	v_pk_mul_f32 v[180:181], v[180:181], v[218:219]
	v_pk_mul_f32 v[182:183], v[182:183], v[208:209]
	v_pk_mul_f32 v[184:185], v[184:185], v[210:211]
	v_pk_mul_f32 v[96:97], v[96:97], v[178:179]
	v_pk_mul_f32 v[98:99], v[98:99], v[180:181]
	v_pk_mul_f32 v[92:93], v[92:93], v[182:183]
	v_pk_mul_f32 v[94:95], v[94:95], v[184:185]
	v_lshlrev_b32_e32 v246, 16, v220
	v_and_b32_e32 v247, 0xffff0000, v220
	v_lshlrev_b32_e32 v248, 16, v221
	v_and_b32_e32 v249, 0xffff0000, v221
	v_lshlrev_b32_e32 v250, 16, v222
	v_and_b32_e32 v251, 0xffff0000, v222
	v_lshlrev_b32_e32 v252, 16, v223
	v_and_b32_e32 v253, 0xffff0000, v223
	v_rcp_f32_e32 v246, v246
	v_rcp_f32_e32 v247, v247
	v_rcp_f32_e32 v248, v248
	v_rcp_f32_e32 v249, v249
	v_rcp_f32_e32 v250, v250
	v_rcp_f32_e32 v251, v251
	v_rcp_f32_e32 v252, v252
	v_rcp_f32_e32 v253, v253
	v_lshlrev_b32_e32 v220, 16, v212
	v_and_b32_e32 v221, 0xffff0000, v212
	v_lshlrev_b32_e32 v222, 16, v213
	v_and_b32_e32 v223, 0xffff0000, v213
	v_lshlrev_b32_e32 v212, 16, v214
	v_and_b32_e32 v213, 0xffff0000, v214
	v_lshlrev_b32_e32 v214, 16, v215
	v_and_b32_e32 v215, 0xffff0000, v215
	v_pk_mul_f32 v[246:247], v[246:247], v[220:221]
	v_pk_mul_f32 v[248:249], v[248:249], v[222:223]
	v_pk_mul_f32 v[250:251], v[250:251], v[212:213]
	v_pk_mul_f32 v[252:253], v[252:253], v[214:215]
	v_pk_mul_f32 v[88:89], v[88:89], v[246:247]
	v_pk_mul_f32 v[90:91], v[90:91], v[248:249]
	v_pk_mul_f32 v[84:85], v[84:85], v[250:251]
	v_pk_mul_f32 v[86:87], v[86:87], v[252:253]
	global_load_dwordx4 v[208:211], v[2:3], off
	global_load_dwordx4 v[212:215], v[2:3], off offset:1024
	global_load_dwordx4 v[216:219], v[254:255], off
	global_load_dwordx4 v[220:223], v[254:255], off offset:1024
	v_lshl_add_u64 v[2:3], v[2:3], 0, s[20:21]
	v_lshl_add_u64 v[254:255], v[254:255], 0, s[20:21]
	s_waitcnt vmcnt(12)
	v_lshlrev_b32_e32 v178, 16, v232
	v_and_b32_e32 v179, 0xffff0000, v232
	v_lshlrev_b32_e32 v180, 16, v233
	v_and_b32_e32 v181, 0xffff0000, v233
	v_lshlrev_b32_e32 v182, 16, v234
	v_and_b32_e32 v183, 0xffff0000, v234
	v_lshlrev_b32_e32 v184, 16, v235
	v_and_b32_e32 v185, 0xffff0000, v235
	v_rcp_f32_e32 v178, v178
	v_rcp_f32_e32 v179, v179
	v_rcp_f32_e32 v180, v180
	v_rcp_f32_e32 v181, v181
	v_rcp_f32_e32 v182, v182
	v_rcp_f32_e32 v183, v183
	v_rcp_f32_e32 v184, v184
	v_rcp_f32_e32 v185, v185
	v_lshlrev_b32_e32 v232, 16, v224
	v_and_b32_e32 v233, 0xffff0000, v224
	v_lshlrev_b32_e32 v234, 16, v225
	v_and_b32_e32 v235, 0xffff0000, v225
	v_lshlrev_b32_e32 v224, 16, v226
	v_and_b32_e32 v225, 0xffff0000, v226
	v_lshlrev_b32_e32 v226, 16, v227
	v_and_b32_e32 v227, 0xffff0000, v227
	v_pk_mul_f32 v[178:179], v[178:179], v[232:233]
	v_pk_mul_f32 v[180:181], v[180:181], v[234:235]
	v_pk_mul_f32 v[182:183], v[182:183], v[224:225]
	v_pk_mul_f32 v[184:185], v[184:185], v[226:227]
	v_pk_mul_f32 v[80:81], v[80:81], v[178:179]
	v_pk_mul_f32 v[82:83], v[82:83], v[180:181]
	v_pk_mul_f32 v[76:77], v[76:77], v[182:183]
	v_pk_mul_f32 v[78:79], v[78:79], v[184:185]
	v_lshlrev_b32_e32 v246, 16, v236
	v_and_b32_e32 v247, 0xffff0000, v236
	v_lshlrev_b32_e32 v248, 16, v237
	v_and_b32_e32 v249, 0xffff0000, v237
	v_lshlrev_b32_e32 v250, 16, v238
	v_and_b32_e32 v251, 0xffff0000, v238
	v_lshlrev_b32_e32 v252, 16, v239
	v_and_b32_e32 v253, 0xffff0000, v239
	v_rcp_f32_e32 v246, v246
	v_rcp_f32_e32 v247, v247
	v_rcp_f32_e32 v248, v248
	v_rcp_f32_e32 v249, v249
	v_rcp_f32_e32 v250, v250
	v_rcp_f32_e32 v251, v251
	v_rcp_f32_e32 v252, v252
	v_rcp_f32_e32 v253, v253
	v_lshlrev_b32_e32 v236, 16, v228
	v_and_b32_e32 v237, 0xffff0000, v228
	v_lshlrev_b32_e32 v238, 16, v229
	v_and_b32_e32 v239, 0xffff0000, v229
	v_lshlrev_b32_e32 v228, 16, v230
	v_and_b32_e32 v229, 0xffff0000, v230
	v_lshlrev_b32_e32 v230, 16, v231
	v_and_b32_e32 v231, 0xffff0000, v231
	v_pk_mul_f32 v[246:247], v[246:247], v[236:237]
	v_pk_mul_f32 v[248:249], v[248:249], v[238:239]
	v_pk_mul_f32 v[250:251], v[250:251], v[228:229]
	v_pk_mul_f32 v[252:253], v[252:253], v[230:231]
	v_pk_mul_f32 v[72:73], v[72:73], v[246:247]
	v_pk_mul_f32 v[74:75], v[74:75], v[248:249]
	v_pk_mul_f32 v[68:69], v[68:69], v[250:251]
	v_pk_mul_f32 v[70:71], v[70:71], v[252:253]
	global_load_dwordx4 v[224:227], v[2:3], off
	global_load_dwordx4 v[228:231], v[2:3], off offset:1024
	global_load_dwordx4 v[232:235], v[254:255], off
	global_load_dwordx4 v[236:239], v[254:255], off offset:1024
	s_waitcnt vmcnt(12)
	v_lshlrev_b32_e32 v178, 16, v140
	v_and_b32_e32 v179, 0xffff0000, v140
	v_lshlrev_b32_e32 v180, 16, v141
	v_and_b32_e32 v181, 0xffff0000, v141
	v_lshlrev_b32_e32 v182, 16, v142
	v_and_b32_e32 v183, 0xffff0000, v142
	v_lshlrev_b32_e32 v184, 16, v143
	v_and_b32_e32 v185, 0xffff0000, v143
	v_rcp_f32_e32 v178, v178
	v_rcp_f32_e32 v179, v179
	v_rcp_f32_e32 v180, v180
	v_rcp_f32_e32 v181, v181
	v_rcp_f32_e32 v182, v182
	v_rcp_f32_e32 v183, v183
	v_rcp_f32_e32 v184, v184
	v_rcp_f32_e32 v185, v185
	v_lshlrev_b32_e32 v140, 16, v132
	v_and_b32_e32 v141, 0xffff0000, v132
	v_lshlrev_b32_e32 v142, 16, v133
	v_and_b32_e32 v143, 0xffff0000, v133
	v_lshlrev_b32_e32 v132, 16, v134
	v_and_b32_e32 v133, 0xffff0000, v134
	v_lshlrev_b32_e32 v134, 16, v135
	v_and_b32_e32 v135, 0xffff0000, v135
	v_pk_mul_f32 v[178:179], v[178:179], v[140:141]
	v_pk_mul_f32 v[180:181], v[180:181], v[142:143]
	v_pk_mul_f32 v[182:183], v[182:183], v[132:133]
	v_pk_mul_f32 v[184:185], v[184:185], v[134:135]
	v_pk_mul_f32 v[64:65], v[64:65], v[178:179]
	v_pk_mul_f32 v[66:67], v[66:67], v[180:181]
	v_pk_mul_f32 v[60:61], v[60:61], v[182:183]
	v_pk_mul_f32 v[62:63], v[62:63], v[184:185]
	v_lshlrev_b32_e32 v246, 16, v188
	v_and_b32_e32 v247, 0xffff0000, v188
	v_lshlrev_b32_e32 v248, 16, v189
	v_and_b32_e32 v249, 0xffff0000, v189
	v_lshlrev_b32_e32 v250, 16, v190
	v_and_b32_e32 v251, 0xffff0000, v190
	v_lshlrev_b32_e32 v252, 16, v191
	v_and_b32_e32 v253, 0xffff0000, v191
	v_rcp_f32_e32 v246, v246
	v_rcp_f32_e32 v247, v247
	v_rcp_f32_e32 v248, v248
	v_rcp_f32_e32 v249, v249
	v_rcp_f32_e32 v250, v250
	v_rcp_f32_e32 v251, v251
	v_rcp_f32_e32 v252, v252
	v_rcp_f32_e32 v253, v253
	v_lshlrev_b32_e32 v188, 16, v136
	v_and_b32_e32 v189, 0xffff0000, v136
	v_lshlrev_b32_e32 v190, 16, v137
	v_and_b32_e32 v191, 0xffff0000, v137
	v_lshlrev_b32_e32 v136, 16, v138
	v_and_b32_e32 v137, 0xffff0000, v138
	v_lshlrev_b32_e32 v138, 16, v139
	v_and_b32_e32 v139, 0xffff0000, v139
	v_pk_mul_f32 v[246:247], v[246:247], v[188:189]
	v_pk_mul_f32 v[248:249], v[248:249], v[190:191]
	v_pk_mul_f32 v[250:251], v[250:251], v[136:137]
	v_pk_mul_f32 v[252:253], v[252:253], v[138:139]
	v_pk_mul_f32 v[56:57], v[56:57], v[246:247]
	v_pk_mul_f32 v[58:59], v[58:59], v[248:249]
	v_pk_mul_f32 v[52:53], v[52:53], v[250:251]
	v_pk_mul_f32 v[54:55], v[54:55], v[252:253]
	s_waitcnt vmcnt(8)
	v_lshlrev_b32_e32 v178, 16, v200
	v_and_b32_e32 v179, 0xffff0000, v200
	v_lshlrev_b32_e32 v180, 16, v201
	v_and_b32_e32 v181, 0xffff0000, v201
	v_lshlrev_b32_e32 v182, 16, v202
	v_and_b32_e32 v183, 0xffff0000, v202
	v_lshlrev_b32_e32 v184, 16, v203
	v_and_b32_e32 v185, 0xffff0000, v203
	v_rcp_f32_e32 v178, v178
	v_rcp_f32_e32 v179, v179
	v_rcp_f32_e32 v180, v180
	v_rcp_f32_e32 v181, v181
	v_rcp_f32_e32 v182, v182
	v_rcp_f32_e32 v183, v183
	v_rcp_f32_e32 v184, v184
	v_rcp_f32_e32 v185, v185
	v_lshlrev_b32_e32 v200, 16, v192
	v_and_b32_e32 v201, 0xffff0000, v192
	v_lshlrev_b32_e32 v202, 16, v193
	v_and_b32_e32 v203, 0xffff0000, v193
	v_lshlrev_b32_e32 v192, 16, v194
	v_and_b32_e32 v193, 0xffff0000, v194
	v_lshlrev_b32_e32 v194, 16, v195
	v_and_b32_e32 v195, 0xffff0000, v195
	v_pk_mul_f32 v[178:179], v[178:179], v[200:201]
	v_pk_mul_f32 v[180:181], v[180:181], v[202:203]
	v_pk_mul_f32 v[182:183], v[182:183], v[192:193]
	v_pk_mul_f32 v[184:185], v[184:185], v[194:195]
	v_pk_mul_f32 v[48:49], v[48:49], v[178:179]
	v_pk_mul_f32 v[50:51], v[50:51], v[180:181]
	v_pk_mul_f32 v[44:45], v[44:45], v[182:183]
	v_pk_mul_f32 v[46:47], v[46:47], v[184:185]
	v_lshlrev_b32_e32 v246, 16, v204
	v_and_b32_e32 v247, 0xffff0000, v204
	v_lshlrev_b32_e32 v248, 16, v205
	v_and_b32_e32 v249, 0xffff0000, v205
	v_lshlrev_b32_e32 v250, 16, v206
	v_and_b32_e32 v251, 0xffff0000, v206
	v_lshlrev_b32_e32 v252, 16, v207
	v_and_b32_e32 v253, 0xffff0000, v207
	v_rcp_f32_e32 v246, v246
	v_rcp_f32_e32 v247, v247
	v_rcp_f32_e32 v248, v248
	v_rcp_f32_e32 v249, v249
	v_rcp_f32_e32 v250, v250
	v_rcp_f32_e32 v251, v251
	v_rcp_f32_e32 v252, v252
	v_rcp_f32_e32 v253, v253
	v_lshlrev_b32_e32 v204, 16, v196
	v_and_b32_e32 v205, 0xffff0000, v196
	v_lshlrev_b32_e32 v206, 16, v197
	v_and_b32_e32 v207, 0xffff0000, v197
	v_lshlrev_b32_e32 v196, 16, v198
	v_and_b32_e32 v197, 0xffff0000, v198
	v_lshlrev_b32_e32 v198, 16, v199
	v_and_b32_e32 v199, 0xffff0000, v199
	v_pk_mul_f32 v[246:247], v[246:247], v[204:205]
	v_pk_mul_f32 v[248:249], v[248:249], v[206:207]
	v_pk_mul_f32 v[250:251], v[250:251], v[196:197]
	v_pk_mul_f32 v[252:253], v[252:253], v[198:199]
	v_pk_mul_f32 v[40:41], v[40:41], v[246:247]
	v_pk_mul_f32 v[42:43], v[42:43], v[248:249]
	v_pk_mul_f32 v[36:37], v[36:37], v[250:251]
	v_pk_mul_f32 v[38:39], v[38:39], v[252:253]
	s_waitcnt vmcnt(4)
	v_lshlrev_b32_e32 v178, 16, v216
	v_and_b32_e32 v179, 0xffff0000, v216
	v_lshlrev_b32_e32 v180, 16, v217
	v_and_b32_e32 v181, 0xffff0000, v217
	v_lshlrev_b32_e32 v182, 16, v218
	v_and_b32_e32 v183, 0xffff0000, v218
	v_lshlrev_b32_e32 v184, 16, v219
	v_and_b32_e32 v185, 0xffff0000, v219
	v_rcp_f32_e32 v178, v178
	v_rcp_f32_e32 v179, v179
	v_rcp_f32_e32 v180, v180
	v_rcp_f32_e32 v181, v181
	v_rcp_f32_e32 v182, v182
	v_rcp_f32_e32 v183, v183
	v_rcp_f32_e32 v184, v184
	v_rcp_f32_e32 v185, v185
	v_lshlrev_b32_e32 v216, 16, v208
	v_and_b32_e32 v217, 0xffff0000, v208
	v_lshlrev_b32_e32 v218, 16, v209
	v_and_b32_e32 v219, 0xffff0000, v209
	v_lshlrev_b32_e32 v208, 16, v210
	v_and_b32_e32 v209, 0xffff0000, v210
	v_lshlrev_b32_e32 v210, 16, v211
	v_and_b32_e32 v211, 0xffff0000, v211
	v_pk_mul_f32 v[178:179], v[178:179], v[216:217]
	v_pk_mul_f32 v[180:181], v[180:181], v[218:219]
	v_pk_mul_f32 v[182:183], v[182:183], v[208:209]
	v_pk_mul_f32 v[184:185], v[184:185], v[210:211]
	v_pk_mul_f32 v[32:33], v[32:33], v[178:179]
	v_pk_mul_f32 v[34:35], v[34:35], v[180:181]
	v_pk_mul_f32 v[28:29], v[28:29], v[182:183]
	v_pk_mul_f32 v[30:31], v[30:31], v[184:185]
	v_lshlrev_b32_e32 v246, 16, v220
	v_and_b32_e32 v247, 0xffff0000, v220
	v_lshlrev_b32_e32 v248, 16, v221
	v_and_b32_e32 v249, 0xffff0000, v221
	v_lshlrev_b32_e32 v250, 16, v222
	v_and_b32_e32 v251, 0xffff0000, v222
	v_lshlrev_b32_e32 v252, 16, v223
	v_and_b32_e32 v253, 0xffff0000, v223
	v_rcp_f32_e32 v246, v246
	v_rcp_f32_e32 v247, v247
	v_rcp_f32_e32 v248, v248
	v_rcp_f32_e32 v249, v249
	v_rcp_f32_e32 v250, v250
	v_rcp_f32_e32 v251, v251
	v_rcp_f32_e32 v252, v252
	v_rcp_f32_e32 v253, v253
	v_lshlrev_b32_e32 v220, 16, v212
	v_and_b32_e32 v221, 0xffff0000, v212
	v_lshlrev_b32_e32 v222, 16, v213
	v_and_b32_e32 v223, 0xffff0000, v213
	v_lshlrev_b32_e32 v212, 16, v214
	v_and_b32_e32 v213, 0xffff0000, v214
	v_lshlrev_b32_e32 v214, 16, v215
	v_and_b32_e32 v215, 0xffff0000, v215
	v_pk_mul_f32 v[246:247], v[246:247], v[220:221]
	v_pk_mul_f32 v[248:249], v[248:249], v[222:223]
	v_pk_mul_f32 v[250:251], v[250:251], v[212:213]
	v_pk_mul_f32 v[252:253], v[252:253], v[214:215]
	v_pk_mul_f32 v[24:25], v[24:25], v[246:247]
	v_pk_mul_f32 v[26:27], v[26:27], v[248:249]
	v_pk_mul_f32 v[20:21], v[20:21], v[250:251]
	v_pk_mul_f32 v[22:23], v[22:23], v[252:253]
	s_waitcnt vmcnt(0)
	v_lshlrev_b32_e32 v178, 16, v232
	v_and_b32_e32 v179, 0xffff0000, v232
	v_lshlrev_b32_e32 v180, 16, v233
	v_and_b32_e32 v181, 0xffff0000, v233
	v_lshlrev_b32_e32 v182, 16, v234
	v_and_b32_e32 v183, 0xffff0000, v234
	v_lshlrev_b32_e32 v184, 16, v235
	v_and_b32_e32 v185, 0xffff0000, v235
	v_rcp_f32_e32 v178, v178
	v_rcp_f32_e32 v179, v179
	v_rcp_f32_e32 v180, v180
	v_rcp_f32_e32 v181, v181
	v_rcp_f32_e32 v182, v182
	v_rcp_f32_e32 v183, v183
	v_rcp_f32_e32 v184, v184
	v_rcp_f32_e32 v185, v185
	v_lshlrev_b32_e32 v232, 16, v224
	v_and_b32_e32 v233, 0xffff0000, v224
	v_lshlrev_b32_e32 v234, 16, v225
	v_and_b32_e32 v235, 0xffff0000, v225
	v_lshlrev_b32_e32 v224, 16, v226
	v_and_b32_e32 v225, 0xffff0000, v226
	v_lshlrev_b32_e32 v226, 16, v227
	v_and_b32_e32 v227, 0xffff0000, v227
	v_pk_mul_f32 v[178:179], v[178:179], v[232:233]
	v_pk_mul_f32 v[180:181], v[180:181], v[234:235]
	v_pk_mul_f32 v[182:183], v[182:183], v[224:225]
	v_pk_mul_f32 v[184:185], v[184:185], v[226:227]
	v_pk_mul_f32 v[16:17], v[16:17], v[178:179]
	v_pk_mul_f32 v[18:19], v[18:19], v[180:181]
	v_pk_mul_f32 v[12:13], v[12:13], v[182:183]
	v_pk_mul_f32 v[14:15], v[14:15], v[184:185]
	v_lshlrev_b32_e32 v246, 16, v236
	v_and_b32_e32 v247, 0xffff0000, v236
	v_lshlrev_b32_e32 v248, 16, v237
	v_and_b32_e32 v249, 0xffff0000, v237
	v_lshlrev_b32_e32 v250, 16, v238
	v_and_b32_e32 v251, 0xffff0000, v238
	v_lshlrev_b32_e32 v252, 16, v239
	v_and_b32_e32 v253, 0xffff0000, v239
	v_rcp_f32_e32 v246, v246
	v_rcp_f32_e32 v247, v247
	v_rcp_f32_e32 v248, v248
	v_rcp_f32_e32 v249, v249
	v_rcp_f32_e32 v250, v250
	v_rcp_f32_e32 v251, v251
	v_rcp_f32_e32 v252, v252
	v_rcp_f32_e32 v253, v253
	v_lshlrev_b32_e32 v236, 16, v228
	v_and_b32_e32 v237, 0xffff0000, v228
	v_lshlrev_b32_e32 v238, 16, v229
	v_and_b32_e32 v239, 0xffff0000, v229
	v_lshlrev_b32_e32 v228, 16, v230
	v_and_b32_e32 v229, 0xffff0000, v230
	v_lshlrev_b32_e32 v230, 16, v231
	v_and_b32_e32 v231, 0xffff0000, v231
	v_pk_mul_f32 v[246:247], v[246:247], v[236:237]
	v_pk_mul_f32 v[248:249], v[248:249], v[238:239]
	v_pk_mul_f32 v[250:251], v[250:251], v[228:229]
	v_pk_mul_f32 v[252:253], v[252:253], v[230:231]
	v_pk_mul_f32 v[8:9], v[8:9], v[246:247]
	v_pk_mul_f32 v[10:11], v[10:11], v[248:249]
	v_pk_mul_f32 v[4:5], v[4:5], v[250:251]
	v_pk_mul_f32 v[6:7], v[6:7], v[252:253]

.LBB0_603:
	s_cmp_gt_i32 s87, 2
	s_mov_b64 s[58:59], -1
	s_cbranch_scc0 .LBB0_605
	s_lshl_b64 s[58:59], s[56:57], 1
	s_mov_b32 s7, s3
	v_mov_b32_e32 v159, v0
	s_add_i32 s99, s98, 2
	s_lshl_b32 s99, s99, 17
	s_add_u32 s100, s38, 0xba00000
	s_addc_u32 s101, s39, 0
	s_add_u32 s100, s100, s99
	s_addc_u32 s101, s101, 0
	v_lshrrev_b32_e32 v2, 6, v175
	v_mul_u32_u24_e32 v2, 0x3c00, v2
	v_lshl_add_u32 v2, v175, 4, v2
	v_mov_b32_e32 v3, 0
	v_lshl_add_u64 v[2:3], s[100:101], 0, v[2:3]
	v_lshlrev_b64 v[140:141], 12, v[164:165]
	v_add_co_u32_e32 v132, vcc, 0, v2
	v_lshl_add_u64 v[140:141], s[10:11], 0, v[140:141]
	s_nop 0
	v_addc_co_u32_e32 v133, vcc, 0, v3, vcc
	v_lshl_add_u64 v[140:141], v[140:141], 0, s[58:59]
	global_load_dwordx4 v[132:135], v[132:133], off
	v_lshl_add_u64 v[136:137], v[2:3], 0, s[24:25]
	v_lshl_add_u64 v[140:141], v[140:141], 0, s[6:7]
	global_load_dwordx4 v[136:139], v[136:137], off offset:1024
	v_lshl_add_u64 v[168:169], v[140:141], 0, v[158:159]
	v_lshl_add_u64 v[2:3], v[2:3], 0, s[26:27]
	flat_load_dwordx4 v[140:143], v[2:3]
	flat_load_dwordx4 v[164:167], v[2:3] offset:1024
	v_lshl_add_u64 v[170:171], v[168:169], 0, s[46:47]
	v_lshl_add_u64 v[2:3], v[2:3], 0, s[20:21]
	s_waitcnt vmcnt(0)
	v_lshlrev_b32_e32 v178, 16, v132
	v_and_b32_e32 v179, 0xffff0000, v132
	v_lshlrev_b32_e32 v132, 16, v133
	v_and_b32_e32 v133, 0xffff0000, v133
	v_lshlrev_b32_e32 v180, 16, v134
	v_and_b32_e32 v181, 0xffff0000, v134
	v_lshlrev_b32_e32 v134, 16, v135
	v_and_b32_e32 v135, 0xffff0000, v135
	v_lshlrev_b32_e32 v182, 16, v136
	v_and_b32_e32 v183, 0xffff0000, v136
	v_lshlrev_b32_e32 v136, 16, v137
	v_and_b32_e32 v137, 0xffff0000, v137
	v_lshlrev_b32_e32 v184, 16, v138
	v_and_b32_e32 v185, 0xffff0000, v138
	v_lshlrev_b32_e32 v138, 16, v139
	v_and_b32_e32 v139, 0xffff0000, v139
	v_pk_mul_f32 v[178:179], v[128:129], v[178:179]
	v_pk_mul_f32 v[188:189], v[130:131], v[132:133]
	v_pk_mul_f32 v[180:181], v[124:125], v[180:181]
	v_pk_mul_f32 v[190:191], v[126:127], v[134:135]
	v_pk_mul_f32 v[182:183], v[120:121], v[182:183]
	v_pk_mul_f32 v[192:193], v[122:123], v[136:137]
	v_pk_mul_f32 v[184:185], v[116:117], v[184:185]
	v_pk_mul_f32 v[194:195], v[118:119], v[138:139]
	v_cvt_pk_bf16_f32 v132, v178, v179
	v_cvt_pk_bf16_f32 v133, v188, v189
	v_cvt_pk_bf16_f32 v134, v180, v181
	v_cvt_pk_bf16_f32 v135, v190, v191
	v_cvt_pk_bf16_f32 v136, v182, v183
	v_cvt_pk_bf16_f32 v137, v192, v193
	v_cvt_pk_bf16_f32 v138, v184, v185
	v_cvt_pk_bf16_f32 v139, v194, v195
	flat_store_dwordx4 v[168:169], v[132:135]
	flat_store_dwordx4 v[168:169], v[136:139] offset:256
	s_waitcnt lgkmcnt(0)
	v_lshlrev_b32_e32 v168, 16, v140
	v_and_b32_e32 v169, 0xffff0000, v140
	v_lshlrev_b32_e32 v140, 16, v141
	v_and_b32_e32 v141, 0xffff0000, v141
	v_lshlrev_b32_e32 v178, 16, v142
	v_and_b32_e32 v179, 0xffff0000, v142
	v_lshlrev_b32_e32 v142, 16, v143
	v_and_b32_e32 v143, 0xffff0000, v143
	v_lshlrev_b32_e32 v180, 16, v164
	v_and_b32_e32 v181, 0xffff0000, v164
	v_lshlrev_b32_e32 v164, 16, v165
	v_and_b32_e32 v165, 0xffff0000, v165
	v_lshlrev_b32_e32 v182, 16, v166
	v_and_b32_e32 v183, 0xffff0000, v166
	v_lshlrev_b32_e32 v166, 16, v167
	v_and_b32_e32 v167, 0xffff0000, v167
	v_pk_mul_f32 v[168:169], v[112:113], v[168:169]
	v_pk_mul_f32 v[184:185], v[114:115], v[140:141]
	v_pk_mul_f32 v[178:179], v[108:109], v[178:179]
	v_pk_mul_f32 v[188:189], v[110:111], v[142:143]
	flat_load_dwordx4 v[132:135], v[2:3]
	flat_load_dwordx4 v[136:139], v[2:3] offset:1024
	v_pk_mul_f32 v[180:181], v[104:105], v[180:181]
	v_pk_mul_f32 v[190:191], v[106:107], v[164:165]
	v_pk_mul_f32 v[182:183], v[100:101], v[182:183]
	v_pk_mul_f32 v[192:193], v[102:103], v[166:167]
	v_cvt_pk_bf16_f32 v140, v168, v169
	v_cvt_pk_bf16_f32 v141, v184, v185
	v_cvt_pk_bf16_f32 v142, v178, v179
	v_cvt_pk_bf16_f32 v143, v188, v189
	v_cvt_pk_bf16_f32 v164, v180, v181
	v_cvt_pk_bf16_f32 v165, v190, v191
	v_cvt_pk_bf16_f32 v166, v182, v183
	v_cvt_pk_bf16_f32 v167, v192, v193
	flat_store_dwordx4 v[170:171], v[140:143]
	flat_store_dwordx4 v[170:171], v[164:167] offset:256
	v_lshl_add_u64 v[168:169], v[170:171], 0, s[46:47]
	v_lshl_add_u64 v[2:3], v[2:3], 0, s[20:21]
	flat_load_dwordx4 v[140:143], v[2:3]
	flat_load_dwordx4 v[164:167], v[2:3] offset:1024
	v_lshl_add_u64 v[170:171], v[168:169], 0, s[46:47]
	v_lshl_add_u64 v[2:3], v[2:3], 0, s[22:23]
	s_waitcnt vmcnt(0) lgkmcnt(0)
	v_lshlrev_b32_e32 v178, 16, v132
	v_and_b32_e32 v179, 0xffff0000, v132
	v_lshlrev_b32_e32 v132, 16, v133
	v_and_b32_e32 v133, 0xffff0000, v133
	v_lshlrev_b32_e32 v180, 16, v134
	v_and_b32_e32 v181, 0xffff0000, v134
	v_lshlrev_b32_e32 v134, 16, v135
	v_and_b32_e32 v135, 0xffff0000, v135
	v_lshlrev_b32_e32 v182, 16, v136
	v_and_b32_e32 v183, 0xffff0000, v136
	v_lshlrev_b32_e32 v136, 16, v137
	v_and_b32_e32 v137, 0xffff0000, v137
	v_lshlrev_b32_e32 v184, 16, v138
	v_and_b32_e32 v185, 0xffff0000, v138
	v_lshlrev_b32_e32 v138, 16, v139
	v_and_b32_e32 v139, 0xffff0000, v139
	v_pk_mul_f32 v[178:179], v[96:97], v[178:179]
	v_pk_mul_f32 v[188:189], v[98:99], v[132:133]
	v_pk_mul_f32 v[180:181], v[92:93], v[180:181]
	v_pk_mul_f32 v[190:191], v[94:95], v[134:135]
	v_pk_mul_f32 v[182:183], v[88:89], v[182:183]
	v_pk_mul_f32 v[192:193], v[90:91], v[136:137]
	v_pk_mul_f32 v[184:185], v[84:85], v[184:185]
	v_pk_mul_f32 v[194:195], v[86:87], v[138:139]
	v_cvt_pk_bf16_f32 v132, v178, v179
	v_cvt_pk_bf16_f32 v133, v188, v189
	v_cvt_pk_bf16_f32 v134, v180, v181
	v_cvt_pk_bf16_f32 v135, v190, v191
	v_cvt_pk_bf16_f32 v136, v182, v183
	v_cvt_pk_bf16_f32 v137, v192, v193
	v_cvt_pk_bf16_f32 v138, v184, v185
	v_cvt_pk_bf16_f32 v139, v194, v195
	flat_store_dwordx4 v[168:169], v[132:135]
	flat_store_dwordx4 v[168:169], v[136:139] offset:256
	v_lshlrev_b32_e32 v168, 16, v140
	v_and_b32_e32 v169, 0xffff0000, v140
	v_lshlrev_b32_e32 v140, 16, v141
	v_and_b32_e32 v141, 0xffff0000, v141
	v_lshlrev_b32_e32 v178, 16, v142
	v_and_b32_e32 v179, 0xffff0000, v142
	v_lshlrev_b32_e32 v142, 16, v143
	v_and_b32_e32 v143, 0xffff0000, v143
	v_lshlrev_b32_e32 v180, 16, v164
	v_and_b32_e32 v181, 0xffff0000, v164
	v_lshlrev_b32_e32 v164, 16, v165
	v_and_b32_e32 v165, 0xffff0000, v165
	v_lshlrev_b32_e32 v182, 16, v166
	v_and_b32_e32 v183, 0xffff0000, v166
	v_lshlrev_b32_e32 v166, 16, v167
	v_and_b32_e32 v167, 0xffff0000, v167
	v_pk_mul_f32 v[168:169], v[80:81], v[168:169]
	v_pk_mul_f32 v[184:185], v[82:83], v[140:141]
	v_pk_mul_f32 v[178:179], v[76:77], v[178:179]
	v_pk_mul_f32 v[188:189], v[78:79], v[142:143]
	flat_load_dwordx4 v[132:135], v[2:3]
	flat_load_dwordx4 v[136:139], v[2:3] offset:1024
	v_pk_mul_f32 v[180:181], v[72:73], v[180:181]
	v_pk_mul_f32 v[190:191], v[74:75], v[164:165]
	v_pk_mul_f32 v[182:183], v[68:69], v[182:183]
	v_pk_mul_f32 v[192:193], v[70:71], v[166:167]
	v_cvt_pk_bf16_f32 v140, v168, v169
	v_cvt_pk_bf16_f32 v141, v184, v185
	v_cvt_pk_bf16_f32 v142, v178, v179
	v_cvt_pk_bf16_f32 v143, v188, v189
	v_cvt_pk_bf16_f32 v164, v180, v181
	v_cvt_pk_bf16_f32 v165, v190, v191
	v_cvt_pk_bf16_f32 v166, v182, v183
	v_cvt_pk_bf16_f32 v167, v192, v193
	flat_store_dwordx4 v[170:171], v[140:143]
	flat_store_dwordx4 v[170:171], v[164:167] offset:256
	v_lshl_add_u64 v[168:169], v[170:171], 0, s[48:49]
	v_lshl_add_u64 v[2:3], v[2:3], 0, s[20:21]
	flat_load_dwordx4 v[140:143], v[2:3]
	flat_load_dwordx4 v[164:167], v[2:3] offset:1024
	v_lshl_add_u64 v[170:171], v[168:169], 0, s[46:47]
	v_lshl_add_u64 v[2:3], v[2:3], 0, s[20:21]
	s_waitcnt vmcnt(0) lgkmcnt(0)
	v_lshlrev_b32_e32 v178, 16, v132
	v_and_b32_e32 v179, 0xffff0000, v132
	v_lshlrev_b32_e32 v132, 16, v133
	v_and_b32_e32 v133, 0xffff0000, v133
	v_lshlrev_b32_e32 v180, 16, v134
	v_and_b32_e32 v181, 0xffff0000, v134
	v_lshlrev_b32_e32 v134, 16, v135
	v_and_b32_e32 v135, 0xffff0000, v135
	v_lshlrev_b32_e32 v182, 16, v136
	v_and_b32_e32 v183, 0xffff0000, v136
	v_lshlrev_b32_e32 v136, 16, v137
	v_and_b32_e32 v137, 0xffff0000, v137
	v_lshlrev_b32_e32 v184, 16, v138
	v_and_b32_e32 v185, 0xffff0000, v138
	v_lshlrev_b32_e32 v138, 16, v139
	v_and_b32_e32 v139, 0xffff0000, v139
	v_pk_mul_f32 v[178:179], v[64:65], v[178:179]
	v_pk_mul_f32 v[188:189], v[66:67], v[132:133]
	v_pk_mul_f32 v[180:181], v[60:61], v[180:181]
	v_pk_mul_f32 v[190:191], v[62:63], v[134:135]
	v_pk_mul_f32 v[182:183], v[56:57], v[182:183]
	v_pk_mul_f32 v[192:193], v[58:59], v[136:137]
	v_pk_mul_f32 v[184:185], v[52:53], v[184:185]
	v_pk_mul_f32 v[194:195], v[54:55], v[138:139]
	v_cvt_pk_bf16_f32 v132, v178, v179
	v_cvt_pk_bf16_f32 v133, v188, v189
	v_cvt_pk_bf16_f32 v134, v180, v181
	v_cvt_pk_bf16_f32 v135, v190, v191
	v_cvt_pk_bf16_f32 v136, v182, v183
	v_cvt_pk_bf16_f32 v137, v192, v193
	v_cvt_pk_bf16_f32 v138, v184, v185
	v_cvt_pk_bf16_f32 v139, v194, v195
	flat_store_dwordx4 v[168:169], v[132:135]
	flat_store_dwordx4 v[168:169], v[136:139] offset:256
	v_lshlrev_b32_e32 v168, 16, v140
	v_and_b32_e32 v169, 0xffff0000, v140
	v_lshlrev_b32_e32 v140, 16, v141
	v_and_b32_e32 v141, 0xffff0000, v141
	v_lshlrev_b32_e32 v178, 16, v142
	v_and_b32_e32 v179, 0xffff0000, v142
	v_lshlrev_b32_e32 v142, 16, v143
	v_and_b32_e32 v143, 0xffff0000, v143
	v_lshlrev_b32_e32 v180, 16, v164
	v_and_b32_e32 v181, 0xffff0000, v164
	v_lshlrev_b32_e32 v164, 16, v165
	v_and_b32_e32 v165, 0xffff0000, v165
	v_lshlrev_b32_e32 v182, 16, v166
	v_and_b32_e32 v183, 0xffff0000, v166
	v_lshlrev_b32_e32 v166, 16, v167
	v_and_b32_e32 v167, 0xffff0000, v167
	v_pk_mul_f32 v[168:169], v[48:49], v[168:169]
	v_pk_mul_f32 v[184:185], v[50:51], v[140:141]
	v_pk_mul_f32 v[178:179], v[44:45], v[178:179]
	v_pk_mul_f32 v[188:189], v[46:47], v[142:143]
	v_pk_mul_f32 v[180:181], v[40:41], v[180:181]
	v_pk_mul_f32 v[190:191], v[42:43], v[164:165]
	v_pk_mul_f32 v[182:183], v[36:37], v[182:183]
	v_pk_mul_f32 v[192:193], v[38:39], v[166:167]
	v_cvt_pk_bf16_f32 v140, v168, v169
	v_cvt_pk_bf16_f32 v141, v184, v185
	v_cvt_pk_bf16_f32 v142, v178, v179
	v_cvt_pk_bf16_f32 v143, v188, v189
	flat_load_dwordx4 v[132:135], v[2:3]
	flat_load_dwordx4 v[136:139], v[2:3] offset:1024
	v_cvt_pk_bf16_f32 v164, v180, v181
	v_cvt_pk_bf16_f32 v165, v190, v191
	v_cvt_pk_bf16_f32 v166, v182, v183
	v_cvt_pk_bf16_f32 v167, v192, v193
	flat_store_dwordx4 v[170:171], v[140:143]
	flat_store_dwordx4 v[170:171], v[164:167] offset:256
	v_lshl_add_u64 v[168:169], v[170:171], 0, s[46:47]
	v_lshl_add_u64 v[170:171], v[2:3], 0, s[20:21]
	flat_load_dwordx4 v[140:143], v[170:171]
	flat_load_dwordx4 v[164:167], v[170:171] offset:1024
	v_lshl_add_u64 v[2:3], v[168:169], 0, s[46:47]
	v_lshl_add_u64 v[170:171], v[170:171], 0, s[22:23]
	s_waitcnt vmcnt(0) lgkmcnt(0)
	v_lshlrev_b32_e32 v178, 16, v132
	v_and_b32_e32 v179, 0xffff0000, v132
	v_lshlrev_b32_e32 v132, 16, v133
	v_and_b32_e32 v133, 0xffff0000, v133
	v_lshlrev_b32_e32 v180, 16, v134
	v_and_b32_e32 v181, 0xffff0000, v134
	v_lshlrev_b32_e32 v134, 16, v135
	v_and_b32_e32 v135, 0xffff0000, v135
	v_lshlrev_b32_e32 v182, 16, v136
	v_and_b32_e32 v183, 0xffff0000, v136
	v_lshlrev_b32_e32 v136, 16, v137
	v_and_b32_e32 v137, 0xffff0000, v137
	v_lshlrev_b32_e32 v184, 16, v138
	v_and_b32_e32 v185, 0xffff0000, v138
	v_lshlrev_b32_e32 v138, 16, v139
	v_and_b32_e32 v139, 0xffff0000, v139
	v_pk_mul_f32 v[178:179], v[32:33], v[178:179]
	v_pk_mul_f32 v[188:189], v[34:35], v[132:133]
	v_pk_mul_f32 v[180:181], v[28:29], v[180:181]
	v_pk_mul_f32 v[190:191], v[30:31], v[134:135]
	v_pk_mul_f32 v[182:183], v[24:25], v[182:183]
	v_pk_mul_f32 v[192:193], v[26:27], v[136:137]
	v_pk_mul_f32 v[184:185], v[20:21], v[184:185]
	v_pk_mul_f32 v[194:195], v[22:23], v[138:139]
	v_cvt_pk_bf16_f32 v132, v178, v179
	v_cvt_pk_bf16_f32 v133, v188, v189
	v_cvt_pk_bf16_f32 v134, v180, v181
	v_cvt_pk_bf16_f32 v135, v190, v191
	v_cvt_pk_bf16_f32 v136, v182, v183
	v_cvt_pk_bf16_f32 v137, v192, v193
	v_cvt_pk_bf16_f32 v138, v184, v185
	v_cvt_pk_bf16_f32 v139, v194, v195
	flat_store_dwordx4 v[168:169], v[132:135]
	flat_store_dwordx4 v[168:169], v[136:139] offset:256
	s_nop 0
	v_lshlrev_b32_e32 v132, 16, v140
	v_and_b32_e32 v133, 0xffff0000, v140
	v_lshlrev_b32_e32 v134, 16, v141
	v_and_b32_e32 v135, 0xffff0000, v141
	v_lshlrev_b32_e32 v136, 16, v142
	v_and_b32_e32 v137, 0xffff0000, v142
	v_lshlrev_b32_e32 v138, 16, v143
	v_and_b32_e32 v139, 0xffff0000, v143
	v_lshlrev_b32_e32 v140, 16, v164
	v_and_b32_e32 v141, 0xffff0000, v164
	v_lshlrev_b32_e32 v142, 16, v165
	v_and_b32_e32 v143, 0xffff0000, v165
	v_lshlrev_b32_e32 v164, 16, v166
	v_and_b32_e32 v165, 0xffff0000, v166
	v_pk_mul_f32 v[132:133], v[16:17], v[132:133]
	v_pk_mul_f32 v[134:135], v[18:19], v[134:135]
	v_pk_mul_f32 v[168:169], v[12:13], v[136:137]
	v_pk_mul_f32 v[170:171], v[14:15], v[138:139]
	v_lshlrev_b32_e32 v166, 16, v167
	v_and_b32_e32 v167, 0xffff0000, v167
	v_pk_mul_f32 v[178:179], v[8:9], v[140:141]
	v_pk_mul_f32 v[142:143], v[10:11], v[142:143]
	v_pk_mul_f32 v[164:165], v[4:5], v[164:165]
	v_cvt_pk_bf16_f32 v138, v132, v133
	v_cvt_pk_bf16_f32 v139, v134, v135
	v_cvt_pk_bf16_f32 v140, v168, v169
	v_cvt_pk_bf16_f32 v141, v170, v171
	v_pk_mul_f32 v[136:137], v[6:7], v[166:167]
	v_cvt_pk_bf16_f32 v132, v178, v179
	v_cvt_pk_bf16_f32 v133, v142, v143
	v_cvt_pk_bf16_f32 v134, v164, v165
	flat_store_dwordx4 v[2:3], v[138:141]
	s_cbranch_execz .LBB0_606
	s_branch .LBB0_607

.LBB0_606:
	v_max_f32_e32 v124, v124, v124
	v_med3_f32 v124, v124, s81, v176
	v_max_f32_e32 v125, v125, v125
	v_mul_f32_e32 v124, 0xbfb8aa3b, v124
	v_med3_f32 v125, v125, s81, v176
	v_exp_f32_e32 v124, v124
	v_mul_f32_e32 v125, 0xbfb8aa3b, v125
	v_exp_f32_e32 v125, v125
	v_max_f32_e32 v1, v128, v128
	v_max_f32_e32 v128, v129, v129
	v_med3_f32 v1, v1, s81, v176
	v_med3_f32 v128, v128, s81, v176
	v_mul_f32_e32 v1, 0xbfb8aa3b, v1
	v_mul_f32_e32 v128, 0xbfb8aa3b, v128
	v_add_f32_e32 v124, 1.0, v124
	v_exp_f32_e32 v1, v1
	v_exp_f32_e32 v128, v128
	v_max_f32_e32 v129, v130, v130
	v_max_f32_e32 v130, v131, v131
	v_rcp_f32_e32 v131, v124
	v_add_f32_e32 v124, 1.0, v125
	v_max_f32_e32 v125, v126, v126
	v_med3_f32 v125, v125, s81, v176
	v_max_f32_e32 v126, v127, v127
	v_mul_f32_e32 v125, 0xbfb8aa3b, v125
	v_med3_f32 v126, v126, s81, v176
	v_exp_f32_e32 v125, v125
	v_mul_f32_e32 v126, 0xbfb8aa3b, v126
	v_add_f32_e32 v1, 1.0, v1
	v_add_f32_e32 v128, 1.0, v128
	v_exp_f32_e32 v126, v126
	v_max_f32_e32 v116, v116, v116
	v_rcp_f32_e32 v1, v1
	v_rcp_f32_e32 v128, v128
	v_med3_f32 v116, v116, s81, v176
	v_max_f32_e32 v117, v117, v117
	v_mul_f32_e32 v116, 0xbfb8aa3b, v116
	v_med3_f32 v117, v117, s81, v176
	v_rcp_f32_e32 v127, v124
	v_add_f32_e32 v124, 1.0, v125
	v_exp_f32_e32 v116, v116
	v_mul_f32_e32 v117, 0xbfb8aa3b, v117
	v_med3_f32 v129, v129, s81, v176
	v_med3_f32 v130, v130, s81, v176
	v_rcp_f32_e32 v132, v124
	v_add_f32_e32 v124, 1.0, v126
	v_exp_f32_e32 v117, v117
	v_mul_f32_e32 v129, 0xbfb8aa3b, v129
	v_mul_f32_e32 v130, 0xbfb8aa3b, v130
	v_rcp_f32_e32 v133, v124
	v_cvt_pk_bf16_f32 v124, v1, v128
	v_max_f32_e32 v1, v120, v120
	v_max_f32_e32 v120, v121, v121
	v_exp_f32_e32 v129, v129
	v_exp_f32_e32 v130, v130
	v_med3_f32 v1, v1, s81, v176
	v_med3_f32 v120, v120, s81, v176
	v_mul_f32_e32 v1, 0xbfb8aa3b, v1
	v_mul_f32_e32 v120, 0xbfb8aa3b, v120
	v_add_f32_e32 v116, 1.0, v116
	v_exp_f32_e32 v1, v1
	v_exp_f32_e32 v120, v120
	v_max_f32_e32 v121, v122, v122
	v_max_f32_e32 v122, v123, v123
	v_rcp_f32_e32 v123, v116
	v_add_f32_e32 v116, 1.0, v117
	v_max_f32_e32 v117, v118, v118
	v_med3_f32 v117, v117, s81, v176
	v_max_f32_e32 v118, v119, v119
	s_lshl_b32 s58, s87, 11
	v_add_f32_e32 v129, 1.0, v129
	v_add_f32_e32 v130, 1.0, v130
	v_mul_f32_e32 v117, 0xbfb8aa3b, v117
	v_med3_f32 v118, v118, s81, v176
	s_ashr_i32 s59, s58, 31
	v_rcp_f32_e32 v129, v129
	v_rcp_f32_e32 v130, v130
	v_exp_f32_e32 v117, v117
	v_mul_f32_e32 v118, 0xbfb8aa3b, v118
	v_add_f32_e32 v1, 1.0, v1
	v_add_f32_e32 v120, 1.0, v120
	v_exp_f32_e32 v118, v118
	v_max_f32_e32 v108, v108, v108
	s_mov_b32 s7, s3
	v_rcp_f32_e32 v1, v1
	v_rcp_f32_e32 v120, v120
	v_med3_f32 v108, v108, s81, v176
	v_max_f32_e32 v109, v109, v109
	v_mov_b32_e32 v159, v0
	v_mul_f32_e32 v108, 0xbfb8aa3b, v108
	v_med3_f32 v109, v109, s81, v176
	s_add_i32 s99, s98, s87
	s_lshl_b32 s99, s99, 17
	s_add_u32 s100, s38, 0xba00000
	s_addc_u32 s101, s39, 0
	s_add_u32 s100, s100, s99
	s_addc_u32 s101, s101, 0
	v_lshrrev_b32_e32 v2, 6, v175
	v_mul_u32_u24_e32 v2, 0x3c00, v2
	v_lshl_add_u32 v2, v175, 4, v2
	v_mov_b32_e32 v3, 0
	v_lshl_add_u64 v[2:3], s[100:101], 0, v[2:3]
	v_cvt_pk_bf16_f32 v125, v129, v130
	v_cvt_pk_bf16_f32 v126, v131, v127
	v_cvt_pk_bf16_f32 v127, v132, v133
	v_rcp_f32_e32 v119, v116
	v_add_f32_e32 v116, 1.0, v117
	v_exp_f32_e32 v108, v108
	v_mul_f32_e32 v109, 0xbfb8aa3b, v109
	flat_store_dwordx4 v[2:3], v[124:127]
	v_med3_f32 v121, v121, s81, v176
	v_med3_f32 v122, v122, s81, v176
	v_rcp_f32_e32 v124, v116
	v_add_f32_e32 v116, 1.0, v118
	v_exp_f32_e32 v109, v109
	v_mul_f32_e32 v121, 0xbfb8aa3b, v121
	v_mul_f32_e32 v122, 0xbfb8aa3b, v122
	v_rcp_f32_e32 v125, v116
	v_cvt_pk_bf16_f32 v116, v1, v120
	v_max_f32_e32 v1, v112, v112
	v_max_f32_e32 v112, v113, v113
	v_exp_f32_e32 v121, v121
	v_exp_f32_e32 v122, v122
	v_med3_f32 v1, v1, s81, v176
	v_med3_f32 v112, v112, s81, v176
	v_mul_f32_e32 v1, 0xbfb8aa3b, v1
	v_mul_f32_e32 v112, 0xbfb8aa3b, v112
	v_add_f32_e32 v108, 1.0, v108
	v_exp_f32_e32 v1, v1
	v_exp_f32_e32 v112, v112
	v_max_f32_e32 v113, v114, v114
	v_max_f32_e32 v114, v115, v115
	v_rcp_f32_e32 v115, v108
	v_add_f32_e32 v108, 1.0, v109
	v_max_f32_e32 v109, v110, v110
	v_med3_f32 v109, v109, s81, v176
	v_max_f32_e32 v110, v111, v111
	v_add_f32_e32 v121, 1.0, v121
	v_add_f32_e32 v122, 1.0, v122
	v_mul_f32_e32 v109, 0xbfb8aa3b, v109
	v_med3_f32 v110, v110, s81, v176
	v_rcp_f32_e32 v121, v121
	v_rcp_f32_e32 v122, v122
	v_exp_f32_e32 v109, v109
	v_mul_f32_e32 v110, 0xbfb8aa3b, v110
	v_add_f32_e32 v1, 1.0, v1
	v_add_f32_e32 v112, 1.0, v112
	v_exp_f32_e32 v110, v110
	v_max_f32_e32 v100, v100, v100
	v_rcp_f32_e32 v1, v1
	v_rcp_f32_e32 v112, v112
	v_med3_f32 v100, v100, s81, v176
	v_max_f32_e32 v101, v101, v101
	v_mul_f32_e32 v100, 0xbfb8aa3b, v100
	v_med3_f32 v101, v101, s81, v176
	v_cvt_pk_bf16_f32 v117, v121, v122
	v_cvt_pk_bf16_f32 v118, v123, v119
	v_cvt_pk_bf16_f32 v119, v124, v125
	v_rcp_f32_e32 v111, v108
	v_add_f32_e32 v108, 1.0, v109
	v_exp_f32_e32 v100, v100
	v_mul_f32_e32 v101, 0xbfb8aa3b, v101
	flat_store_dwordx4 v[2:3], v[116:119] offset:1024
	v_med3_f32 v113, v113, s81, v176
	v_med3_f32 v114, v114, s81, v176
	v_rcp_f32_e32 v116, v108
	v_add_f32_e32 v108, 1.0, v110
	v_exp_f32_e32 v101, v101
	v_mul_f32_e32 v113, 0xbfb8aa3b, v113
	v_mul_f32_e32 v114, 0xbfb8aa3b, v114
	v_rcp_f32_e32 v117, v108
	v_cvt_pk_bf16_f32 v108, v1, v112
	v_max_f32_e32 v1, v104, v104
	v_max_f32_e32 v104, v105, v105
	v_exp_f32_e32 v113, v113
	v_exp_f32_e32 v114, v114
	v_med3_f32 v1, v1, s81, v176
	v_med3_f32 v104, v104, s81, v176
	v_mul_f32_e32 v1, 0xbfb8aa3b, v1
	v_mul_f32_e32 v104, 0xbfb8aa3b, v104
	v_add_f32_e32 v100, 1.0, v100
	v_exp_f32_e32 v1, v1
	v_exp_f32_e32 v104, v104
	v_max_f32_e32 v105, v106, v106
	v_max_f32_e32 v106, v107, v107
	v_rcp_f32_e32 v107, v100
	v_add_f32_e32 v100, 1.0, v101
	v_max_f32_e32 v101, v102, v102
	v_med3_f32 v101, v101, s81, v176
	v_max_f32_e32 v102, v103, v103
	v_add_f32_e32 v113, 1.0, v113
	v_add_f32_e32 v114, 1.0, v114
	v_mul_f32_e32 v101, 0xbfb8aa3b, v101
	v_med3_f32 v102, v102, s81, v176
	v_rcp_f32_e32 v113, v113
	v_rcp_f32_e32 v114, v114
	v_exp_f32_e32 v101, v101
	v_mul_f32_e32 v102, 0xbfb8aa3b, v102
	v_add_f32_e32 v1, 1.0, v1
	v_add_f32_e32 v104, 1.0, v104
	v_exp_f32_e32 v102, v102
	v_max_f32_e32 v92, v92, v92
	v_rcp_f32_e32 v1, v1
	v_rcp_f32_e32 v104, v104
	v_med3_f32 v92, v92, s81, v176
	v_max_f32_e32 v93, v93, v93
	v_mul_f32_e32 v92, 0xbfb8aa3b, v92
	v_med3_f32 v93, v93, s81, v176
	v_lshl_add_u64 v[2:3], v[2:3], 0, s[20:21]
	v_cvt_pk_bf16_f32 v109, v113, v114
	v_cvt_pk_bf16_f32 v110, v115, v111
	v_cvt_pk_bf16_f32 v111, v116, v117
	v_rcp_f32_e32 v103, v100
	v_add_f32_e32 v100, 1.0, v101
	v_exp_f32_e32 v92, v92
	v_mul_f32_e32 v93, 0xbfb8aa3b, v93
	flat_store_dwordx4 v[2:3], v[108:111]
	v_med3_f32 v105, v105, s81, v176
	v_med3_f32 v106, v106, s81, v176
	v_rcp_f32_e32 v108, v100
	v_add_f32_e32 v100, 1.0, v102
	v_exp_f32_e32 v93, v93
	v_mul_f32_e32 v105, 0xbfb8aa3b, v105
	v_mul_f32_e32 v106, 0xbfb8aa3b, v106
	v_rcp_f32_e32 v109, v100
	v_cvt_pk_bf16_f32 v100, v1, v104
	v_max_f32_e32 v1, v96, v96
	v_max_f32_e32 v96, v97, v97
	v_exp_f32_e32 v105, v105
	v_exp_f32_e32 v106, v106
	v_med3_f32 v1, v1, s81, v176
	v_med3_f32 v96, v96, s81, v176
	v_mul_f32_e32 v1, 0xbfb8aa3b, v1
	v_mul_f32_e32 v96, 0xbfb8aa3b, v96
	v_add_f32_e32 v92, 1.0, v92
	v_exp_f32_e32 v1, v1
	v_exp_f32_e32 v96, v96
	v_max_f32_e32 v97, v98, v98
	v_max_f32_e32 v98, v99, v99
	v_rcp_f32_e32 v99, v92
	v_add_f32_e32 v92, 1.0, v93
	v_max_f32_e32 v93, v94, v94
	v_med3_f32 v93, v93, s81, v176
	v_max_f32_e32 v94, v95, v95
	v_add_f32_e32 v105, 1.0, v105
	v_add_f32_e32 v106, 1.0, v106
	v_mul_f32_e32 v93, 0xbfb8aa3b, v93
	v_med3_f32 v94, v94, s81, v176
	v_rcp_f32_e32 v105, v105
	v_rcp_f32_e32 v106, v106
	v_exp_f32_e32 v93, v93
	v_mul_f32_e32 v94, 0xbfb8aa3b, v94
	v_add_f32_e32 v1, 1.0, v1
	v_add_f32_e32 v96, 1.0, v96
	v_exp_f32_e32 v94, v94
	v_max_f32_e32 v84, v84, v84
	v_rcp_f32_e32 v1, v1
	v_rcp_f32_e32 v96, v96
	v_med3_f32 v84, v84, s81, v176
	v_max_f32_e32 v85, v85, v85
	v_mul_f32_e32 v84, 0xbfb8aa3b, v84
	v_med3_f32 v85, v85, s81, v176
	v_cvt_pk_bf16_f32 v101, v105, v106
	v_cvt_pk_bf16_f32 v102, v107, v103
	v_cvt_pk_bf16_f32 v103, v108, v109
	v_rcp_f32_e32 v95, v92
	v_add_f32_e32 v92, 1.0, v93
	v_exp_f32_e32 v84, v84
	v_mul_f32_e32 v85, 0xbfb8aa3b, v85
	flat_store_dwordx4 v[2:3], v[100:103] offset:1024
	v_med3_f32 v97, v97, s81, v176
	v_med3_f32 v98, v98, s81, v176
	v_rcp_f32_e32 v100, v92
	v_add_f32_e32 v92, 1.0, v94
	v_exp_f32_e32 v85, v85
	v_mul_f32_e32 v97, 0xbfb8aa3b, v97
	v_mul_f32_e32 v98, 0xbfb8aa3b, v98
	v_rcp_f32_e32 v101, v92
	v_cvt_pk_bf16_f32 v92, v1, v96
	v_max_f32_e32 v1, v88, v88
	v_max_f32_e32 v88, v89, v89
	v_exp_f32_e32 v97, v97
	v_exp_f32_e32 v98, v98
	v_med3_f32 v1, v1, s81, v176
	v_med3_f32 v88, v88, s81, v176
	v_mul_f32_e32 v1, 0xbfb8aa3b, v1
	v_mul_f32_e32 v88, 0xbfb8aa3b, v88
	v_add_f32_e32 v84, 1.0, v84
	v_exp_f32_e32 v1, v1
	v_exp_f32_e32 v88, v88
	v_max_f32_e32 v89, v90, v90
	v_max_f32_e32 v90, v91, v91
	v_rcp_f32_e32 v91, v84
	v_add_f32_e32 v84, 1.0, v85
	v_max_f32_e32 v85, v86, v86
	v_med3_f32 v85, v85, s81, v176
	v_max_f32_e32 v86, v87, v87
	v_add_f32_e32 v97, 1.0, v97
	v_add_f32_e32 v98, 1.0, v98
	v_mul_f32_e32 v85, 0xbfb8aa3b, v85
	v_med3_f32 v86, v86, s81, v176
	v_rcp_f32_e32 v97, v97
	v_rcp_f32_e32 v98, v98
	v_exp_f32_e32 v85, v85
	v_mul_f32_e32 v86, 0xbfb8aa3b, v86
	v_add_f32_e32 v1, 1.0, v1
	v_add_f32_e32 v88, 1.0, v88
	v_exp_f32_e32 v86, v86
	v_max_f32_e32 v76, v76, v76
	v_rcp_f32_e32 v1, v1
	v_rcp_f32_e32 v88, v88
	v_med3_f32 v76, v76, s81, v176
	v_max_f32_e32 v77, v77, v77
	v_mul_f32_e32 v76, 0xbfb8aa3b, v76
	v_med3_f32 v77, v77, s81, v176
	v_lshl_add_u64 v[2:3], v[2:3], 0, s[20:21]
	v_cvt_pk_bf16_f32 v93, v97, v98
	v_cvt_pk_bf16_f32 v94, v99, v95
	v_cvt_pk_bf16_f32 v95, v100, v101
	v_rcp_f32_e32 v87, v84
	v_add_f32_e32 v84, 1.0, v85
	v_exp_f32_e32 v76, v76
	v_mul_f32_e32 v77, 0xbfb8aa3b, v77
	flat_store_dwordx4 v[2:3], v[92:95]
	v_med3_f32 v89, v89, s81, v176
	v_med3_f32 v90, v90, s81, v176
	v_rcp_f32_e32 v92, v84
	v_add_f32_e32 v84, 1.0, v86
	v_exp_f32_e32 v77, v77
	v_mul_f32_e32 v89, 0xbfb8aa3b, v89
	v_mul_f32_e32 v90, 0xbfb8aa3b, v90
	v_rcp_f32_e32 v93, v84
	v_cvt_pk_bf16_f32 v84, v1, v88
	v_max_f32_e32 v1, v80, v80
	v_max_f32_e32 v80, v81, v81
	v_exp_f32_e32 v89, v89
	v_exp_f32_e32 v90, v90
	v_med3_f32 v1, v1, s81, v176
	v_med3_f32 v80, v80, s81, v176
	v_mul_f32_e32 v1, 0xbfb8aa3b, v1
	v_mul_f32_e32 v80, 0xbfb8aa3b, v80
	v_add_f32_e32 v76, 1.0, v76
	v_exp_f32_e32 v1, v1
	v_exp_f32_e32 v80, v80
	v_max_f32_e32 v81, v82, v82
	v_max_f32_e32 v82, v83, v83
	v_rcp_f32_e32 v83, v76
	v_add_f32_e32 v76, 1.0, v77
	v_max_f32_e32 v77, v78, v78
	v_med3_f32 v77, v77, s81, v176
	v_max_f32_e32 v78, v79, v79
	v_add_f32_e32 v89, 1.0, v89
	v_add_f32_e32 v90, 1.0, v90
	v_mul_f32_e32 v77, 0xbfb8aa3b, v77
	v_med3_f32 v78, v78, s81, v176
	v_rcp_f32_e32 v89, v89
	v_rcp_f32_e32 v90, v90
	v_exp_f32_e32 v77, v77
	v_mul_f32_e32 v78, 0xbfb8aa3b, v78
	v_add_f32_e32 v1, 1.0, v1
	v_add_f32_e32 v80, 1.0, v80
	v_exp_f32_e32 v78, v78
	v_max_f32_e32 v68, v68, v68
	v_rcp_f32_e32 v1, v1
	v_rcp_f32_e32 v80, v80
	v_med3_f32 v68, v68, s81, v176
	v_max_f32_e32 v69, v69, v69
	v_mul_f32_e32 v68, 0xbfb8aa3b, v68
	v_med3_f32 v69, v69, s81, v176
	v_cvt_pk_bf16_f32 v85, v89, v90
	v_cvt_pk_bf16_f32 v86, v91, v87
	v_cvt_pk_bf16_f32 v87, v92, v93
	v_rcp_f32_e32 v79, v76
	v_add_f32_e32 v76, 1.0, v77
	v_exp_f32_e32 v68, v68
	v_mul_f32_e32 v69, 0xbfb8aa3b, v69
	flat_store_dwordx4 v[2:3], v[84:87] offset:1024
	v_med3_f32 v81, v81, s81, v176
	v_med3_f32 v82, v82, s81, v176
	v_rcp_f32_e32 v84, v76
	v_add_f32_e32 v76, 1.0, v78
	v_exp_f32_e32 v69, v69
	v_mul_f32_e32 v81, 0xbfb8aa3b, v81
	v_mul_f32_e32 v82, 0xbfb8aa3b, v82
	v_rcp_f32_e32 v85, v76
	v_cvt_pk_bf16_f32 v76, v1, v80
	v_max_f32_e32 v1, v72, v72
	v_max_f32_e32 v72, v73, v73
	v_exp_f32_e32 v81, v81
	v_exp_f32_e32 v82, v82
	v_med3_f32 v1, v1, s81, v176
	v_med3_f32 v72, v72, s81, v176
	v_mul_f32_e32 v1, 0xbfb8aa3b, v1
	v_mul_f32_e32 v72, 0xbfb8aa3b, v72
	v_add_f32_e32 v68, 1.0, v68
	v_exp_f32_e32 v1, v1
	v_exp_f32_e32 v72, v72
	v_max_f32_e32 v73, v74, v74
	v_max_f32_e32 v74, v75, v75
	v_rcp_f32_e32 v75, v68
	v_add_f32_e32 v68, 1.0, v69
	v_max_f32_e32 v69, v70, v70
	v_med3_f32 v69, v69, s81, v176
	v_max_f32_e32 v70, v71, v71
	v_add_f32_e32 v81, 1.0, v81
	v_add_f32_e32 v82, 1.0, v82
	v_mul_f32_e32 v69, 0xbfb8aa3b, v69
	v_med3_f32 v70, v70, s81, v176
	v_rcp_f32_e32 v81, v81
	v_rcp_f32_e32 v82, v82
	v_exp_f32_e32 v69, v69
	v_mul_f32_e32 v70, 0xbfb8aa3b, v70
	v_add_f32_e32 v1, 1.0, v1
	v_add_f32_e32 v72, 1.0, v72
	v_exp_f32_e32 v70, v70
	v_max_f32_e32 v60, v60, v60
	v_rcp_f32_e32 v1, v1
	v_rcp_f32_e32 v72, v72
	v_med3_f32 v60, v60, s81, v176
	v_max_f32_e32 v61, v61, v61
	v_mul_f32_e32 v60, 0xbfb8aa3b, v60
	v_med3_f32 v61, v61, s81, v176
	v_lshl_add_u64 v[2:3], v[2:3], 0, s[20:21]
	v_cvt_pk_bf16_f32 v77, v81, v82
	v_cvt_pk_bf16_f32 v78, v83, v79
	v_cvt_pk_bf16_f32 v79, v84, v85
	v_rcp_f32_e32 v71, v68
	v_add_f32_e32 v68, 1.0, v69
	v_exp_f32_e32 v60, v60
	v_mul_f32_e32 v61, 0xbfb8aa3b, v61
	flat_store_dwordx4 v[2:3], v[76:79]
	v_med3_f32 v73, v73, s81, v176
	v_med3_f32 v74, v74, s81, v176
	v_rcp_f32_e32 v76, v68
	v_add_f32_e32 v68, 1.0, v70
	v_exp_f32_e32 v61, v61
	v_mul_f32_e32 v73, 0xbfb8aa3b, v73
	v_mul_f32_e32 v74, 0xbfb8aa3b, v74
	v_rcp_f32_e32 v77, v68
	v_cvt_pk_bf16_f32 v68, v1, v72
	v_max_f32_e32 v1, v64, v64
	v_max_f32_e32 v64, v65, v65
	v_exp_f32_e32 v73, v73
	v_exp_f32_e32 v74, v74
	v_med3_f32 v1, v1, s81, v176
	v_med3_f32 v64, v64, s81, v176
	v_mul_f32_e32 v1, 0xbfb8aa3b, v1
	v_mul_f32_e32 v64, 0xbfb8aa3b, v64
	v_add_f32_e32 v60, 1.0, v60
	v_exp_f32_e32 v1, v1
	v_exp_f32_e32 v64, v64
	v_max_f32_e32 v65, v66, v66
	v_max_f32_e32 v66, v67, v67
	v_rcp_f32_e32 v67, v60
	v_add_f32_e32 v60, 1.0, v61
	v_max_f32_e32 v61, v62, v62
	v_med3_f32 v61, v61, s81, v176
	v_max_f32_e32 v62, v63, v63
	v_add_f32_e32 v73, 1.0, v73
	v_add_f32_e32 v74, 1.0, v74
	v_mul_f32_e32 v61, 0xbfb8aa3b, v61
	v_med3_f32 v62, v62, s81, v176
	v_rcp_f32_e32 v73, v73
	v_rcp_f32_e32 v74, v74
	v_exp_f32_e32 v61, v61
	v_mul_f32_e32 v62, 0xbfb8aa3b, v62
	v_add_f32_e32 v1, 1.0, v1
	v_add_f32_e32 v64, 1.0, v64
	v_exp_f32_e32 v62, v62
	v_max_f32_e32 v52, v52, v52
	v_rcp_f32_e32 v1, v1
	v_rcp_f32_e32 v64, v64
	v_med3_f32 v52, v52, s81, v176
	v_max_f32_e32 v53, v53, v53
	v_mul_f32_e32 v52, 0xbfb8aa3b, v52
	v_med3_f32 v53, v53, s81, v176
	v_cvt_pk_bf16_f32 v69, v73, v74
	v_cvt_pk_bf16_f32 v70, v75, v71
	v_cvt_pk_bf16_f32 v71, v76, v77
	v_rcp_f32_e32 v63, v60
	v_add_f32_e32 v60, 1.0, v61
	v_exp_f32_e32 v52, v52
	v_mul_f32_e32 v53, 0xbfb8aa3b, v53
	flat_store_dwordx4 v[2:3], v[68:71] offset:1024
	v_med3_f32 v65, v65, s81, v176
	v_med3_f32 v66, v66, s81, v176
	v_rcp_f32_e32 v68, v60
	v_add_f32_e32 v60, 1.0, v62
	v_exp_f32_e32 v53, v53
	v_mul_f32_e32 v65, 0xbfb8aa3b, v65
	v_mul_f32_e32 v66, 0xbfb8aa3b, v66
	v_rcp_f32_e32 v69, v60
	v_cvt_pk_bf16_f32 v60, v1, v64
	v_max_f32_e32 v1, v56, v56
	v_max_f32_e32 v56, v57, v57
	v_exp_f32_e32 v65, v65
	v_exp_f32_e32 v66, v66
	v_med3_f32 v1, v1, s81, v176
	v_med3_f32 v56, v56, s81, v176
	v_mul_f32_e32 v1, 0xbfb8aa3b, v1
	v_mul_f32_e32 v56, 0xbfb8aa3b, v56
	v_add_f32_e32 v52, 1.0, v52
	v_exp_f32_e32 v1, v1
	v_exp_f32_e32 v56, v56
	v_max_f32_e32 v57, v58, v58
	v_max_f32_e32 v58, v59, v59
	v_rcp_f32_e32 v59, v52
	v_add_f32_e32 v52, 1.0, v53
	v_max_f32_e32 v53, v54, v54
	v_med3_f32 v53, v53, s81, v176
	v_max_f32_e32 v54, v55, v55
	v_add_f32_e32 v65, 1.0, v65
	v_add_f32_e32 v66, 1.0, v66
	v_mul_f32_e32 v53, 0xbfb8aa3b, v53
	v_med3_f32 v54, v54, s81, v176
	v_rcp_f32_e32 v65, v65
	v_rcp_f32_e32 v66, v66
	v_exp_f32_e32 v53, v53
	v_mul_f32_e32 v54, 0xbfb8aa3b, v54
	v_add_f32_e32 v1, 1.0, v1
	v_add_f32_e32 v56, 1.0, v56
	v_exp_f32_e32 v54, v54
	v_max_f32_e32 v44, v44, v44
	v_rcp_f32_e32 v1, v1
	v_rcp_f32_e32 v56, v56
	v_med3_f32 v44, v44, s81, v176
	v_max_f32_e32 v45, v45, v45
	v_mul_f32_e32 v44, 0xbfb8aa3b, v44
	v_med3_f32 v45, v45, s81, v176
	v_lshl_add_u64 v[2:3], v[2:3], 0, s[22:23]
	v_cvt_pk_bf16_f32 v61, v65, v66
	v_cvt_pk_bf16_f32 v62, v67, v63
	v_cvt_pk_bf16_f32 v63, v68, v69
	v_rcp_f32_e32 v55, v52
	v_add_f32_e32 v52, 1.0, v53
	v_exp_f32_e32 v44, v44
	v_mul_f32_e32 v45, 0xbfb8aa3b, v45
	flat_store_dwordx4 v[2:3], v[60:63]
	v_med3_f32 v57, v57, s81, v176
	v_med3_f32 v58, v58, s81, v176
	v_rcp_f32_e32 v60, v52
	v_add_f32_e32 v52, 1.0, v54
	v_exp_f32_e32 v45, v45
	v_mul_f32_e32 v57, 0xbfb8aa3b, v57
	v_mul_f32_e32 v58, 0xbfb8aa3b, v58
	v_rcp_f32_e32 v61, v52
	v_cvt_pk_bf16_f32 v52, v1, v56
	v_max_f32_e32 v1, v48, v48
	v_max_f32_e32 v48, v49, v49
	v_exp_f32_e32 v57, v57
	v_exp_f32_e32 v58, v58
	v_med3_f32 v1, v1, s81, v176
	v_med3_f32 v48, v48, s81, v176
	v_mul_f32_e32 v1, 0xbfb8aa3b, v1
	v_mul_f32_e32 v48, 0xbfb8aa3b, v48
	v_add_f32_e32 v44, 1.0, v44
	v_exp_f32_e32 v1, v1
	v_exp_f32_e32 v48, v48
	v_max_f32_e32 v49, v50, v50
	v_max_f32_e32 v50, v51, v51
	v_rcp_f32_e32 v51, v44
	v_add_f32_e32 v44, 1.0, v45
	v_max_f32_e32 v45, v46, v46
	v_med3_f32 v45, v45, s81, v176
	v_max_f32_e32 v46, v47, v47
	v_add_f32_e32 v57, 1.0, v57
	v_add_f32_e32 v58, 1.0, v58
	v_mul_f32_e32 v45, 0xbfb8aa3b, v45
	v_med3_f32 v46, v46, s81, v176
	v_rcp_f32_e32 v57, v57
	v_rcp_f32_e32 v58, v58
	v_exp_f32_e32 v45, v45
	v_mul_f32_e32 v46, 0xbfb8aa3b, v46
	v_add_f32_e32 v1, 1.0, v1
	v_add_f32_e32 v48, 1.0, v48
	v_exp_f32_e32 v46, v46
	v_max_f32_e32 v36, v36, v36
	v_rcp_f32_e32 v1, v1
	v_rcp_f32_e32 v48, v48
	v_med3_f32 v36, v36, s81, v176
	v_max_f32_e32 v37, v37, v37
	v_mul_f32_e32 v36, 0xbfb8aa3b, v36
	v_med3_f32 v37, v37, s81, v176
	v_cvt_pk_bf16_f32 v53, v57, v58
	v_cvt_pk_bf16_f32 v54, v59, v55
	v_cvt_pk_bf16_f32 v55, v60, v61
	v_rcp_f32_e32 v47, v44
	v_add_f32_e32 v44, 1.0, v45
	v_exp_f32_e32 v36, v36
	v_mul_f32_e32 v37, 0xbfb8aa3b, v37
	flat_store_dwordx4 v[2:3], v[52:55] offset:1024
	v_med3_f32 v49, v49, s81, v176
	v_med3_f32 v50, v50, s81, v176
	v_rcp_f32_e32 v52, v44
	v_add_f32_e32 v44, 1.0, v46
	v_exp_f32_e32 v37, v37
	v_mul_f32_e32 v49, 0xbfb8aa3b, v49
	v_mul_f32_e32 v50, 0xbfb8aa3b, v50
	v_rcp_f32_e32 v53, v44
	v_cvt_pk_bf16_f32 v44, v1, v48
	v_max_f32_e32 v1, v40, v40
	v_max_f32_e32 v40, v41, v41
	v_exp_f32_e32 v49, v49
	v_exp_f32_e32 v50, v50
	v_med3_f32 v1, v1, s81, v176
	v_med3_f32 v40, v40, s81, v176
	v_mul_f32_e32 v1, 0xbfb8aa3b, v1
	v_mul_f32_e32 v40, 0xbfb8aa3b, v40
	v_add_f32_e32 v36, 1.0, v36
	v_exp_f32_e32 v1, v1
	v_exp_f32_e32 v40, v40
	v_max_f32_e32 v41, v42, v42
	v_max_f32_e32 v42, v43, v43
	v_rcp_f32_e32 v43, v36
	v_add_f32_e32 v36, 1.0, v37
	v_max_f32_e32 v37, v38, v38
	v_med3_f32 v37, v37, s81, v176
	v_max_f32_e32 v38, v39, v39
	v_add_f32_e32 v49, 1.0, v49
	v_add_f32_e32 v50, 1.0, v50
	v_mul_f32_e32 v37, 0xbfb8aa3b, v37
	v_med3_f32 v38, v38, s81, v176
	v_rcp_f32_e32 v49, v49
	v_rcp_f32_e32 v50, v50
	v_exp_f32_e32 v37, v37
	v_mul_f32_e32 v38, 0xbfb8aa3b, v38
	v_add_f32_e32 v1, 1.0, v1
	v_add_f32_e32 v40, 1.0, v40
	v_exp_f32_e32 v38, v38
	v_max_f32_e32 v28, v28, v28
	v_rcp_f32_e32 v1, v1
	v_rcp_f32_e32 v40, v40
	v_med3_f32 v28, v28, s81, v176
	v_max_f32_e32 v29, v29, v29
	v_mul_f32_e32 v28, 0xbfb8aa3b, v28
	v_med3_f32 v29, v29, s81, v176
	v_lshl_add_u64 v[2:3], v[2:3], 0, s[20:21]
	v_cvt_pk_bf16_f32 v45, v49, v50
	v_cvt_pk_bf16_f32 v46, v51, v47
	v_cvt_pk_bf16_f32 v47, v52, v53
	v_rcp_f32_e32 v39, v36
	v_add_f32_e32 v36, 1.0, v37
	v_exp_f32_e32 v28, v28
	v_mul_f32_e32 v29, 0xbfb8aa3b, v29
	flat_store_dwordx4 v[2:3], v[44:47]
	v_med3_f32 v41, v41, s81, v176
	v_med3_f32 v42, v42, s81, v176
	v_rcp_f32_e32 v44, v36
	v_add_f32_e32 v36, 1.0, v38
	v_exp_f32_e32 v29, v29
	v_mul_f32_e32 v41, 0xbfb8aa3b, v41
	v_mul_f32_e32 v42, 0xbfb8aa3b, v42
	v_rcp_f32_e32 v45, v36
	v_cvt_pk_bf16_f32 v36, v1, v40
	v_max_f32_e32 v1, v32, v32
	v_max_f32_e32 v32, v33, v33
	v_exp_f32_e32 v41, v41
	v_exp_f32_e32 v42, v42
	v_med3_f32 v1, v1, s81, v176
	v_med3_f32 v32, v32, s81, v176
	v_mul_f32_e32 v1, 0xbfb8aa3b, v1
	v_mul_f32_e32 v32, 0xbfb8aa3b, v32
	v_add_f32_e32 v28, 1.0, v28
	v_exp_f32_e32 v1, v1
	v_exp_f32_e32 v32, v32
	v_max_f32_e32 v33, v34, v34
	v_max_f32_e32 v34, v35, v35
	v_rcp_f32_e32 v35, v28
	v_add_f32_e32 v28, 1.0, v29
	v_max_f32_e32 v29, v30, v30
	v_med3_f32 v29, v29, s81, v176
	v_max_f32_e32 v30, v31, v31
	v_add_f32_e32 v41, 1.0, v41
	v_add_f32_e32 v42, 1.0, v42
	v_mul_f32_e32 v29, 0xbfb8aa3b, v29
	v_med3_f32 v30, v30, s81, v176
	v_rcp_f32_e32 v41, v41
	v_rcp_f32_e32 v42, v42
	v_exp_f32_e32 v29, v29
	v_mul_f32_e32 v30, 0xbfb8aa3b, v30
	v_add_f32_e32 v1, 1.0, v1
	v_add_f32_e32 v32, 1.0, v32
	v_exp_f32_e32 v30, v30
	v_max_f32_e32 v20, v20, v20
	v_rcp_f32_e32 v1, v1
	v_rcp_f32_e32 v32, v32
	v_med3_f32 v20, v20, s81, v176
	v_max_f32_e32 v21, v21, v21
	v_mul_f32_e32 v20, 0xbfb8aa3b, v20
	v_med3_f32 v21, v21, s81, v176
	v_cvt_pk_bf16_f32 v37, v41, v42
	v_cvt_pk_bf16_f32 v38, v43, v39
	v_cvt_pk_bf16_f32 v39, v44, v45
	v_rcp_f32_e32 v31, v28
	v_add_f32_e32 v28, 1.0, v29
	v_exp_f32_e32 v20, v20
	v_mul_f32_e32 v21, 0xbfb8aa3b, v21
	flat_store_dwordx4 v[2:3], v[36:39] offset:1024
	v_med3_f32 v33, v33, s81, v176
	v_med3_f32 v34, v34, s81, v176
	v_rcp_f32_e32 v36, v28
	v_add_f32_e32 v28, 1.0, v30
	v_exp_f32_e32 v21, v21
	v_mul_f32_e32 v33, 0xbfb8aa3b, v33
	v_mul_f32_e32 v34, 0xbfb8aa3b, v34
	v_rcp_f32_e32 v37, v28
	v_cvt_pk_bf16_f32 v28, v1, v32
	v_max_f32_e32 v1, v24, v24
	v_max_f32_e32 v24, v25, v25
	v_exp_f32_e32 v33, v33
	v_exp_f32_e32 v34, v34
	v_med3_f32 v1, v1, s81, v176
	v_med3_f32 v24, v24, s81, v176
	v_mul_f32_e32 v1, 0xbfb8aa3b, v1
	v_mul_f32_e32 v24, 0xbfb8aa3b, v24
	v_add_f32_e32 v20, 1.0, v20
	v_exp_f32_e32 v1, v1
	v_exp_f32_e32 v24, v24
	v_max_f32_e32 v25, v26, v26
	v_max_f32_e32 v26, v27, v27
	v_rcp_f32_e32 v27, v20
	v_add_f32_e32 v20, 1.0, v21
	v_max_f32_e32 v21, v22, v22
	v_med3_f32 v21, v21, s81, v176
	v_max_f32_e32 v22, v23, v23
	v_add_f32_e32 v33, 1.0, v33
	v_add_f32_e32 v34, 1.0, v34
	v_mul_f32_e32 v21, 0xbfb8aa3b, v21
	v_med3_f32 v22, v22, s81, v176
	v_rcp_f32_e32 v33, v33
	v_rcp_f32_e32 v34, v34
	v_exp_f32_e32 v21, v21
	v_mul_f32_e32 v22, 0xbfb8aa3b, v22
	v_add_f32_e32 v1, 1.0, v1
	v_add_f32_e32 v24, 1.0, v24
	v_exp_f32_e32 v22, v22
	v_max_f32_e32 v12, v12, v12
	v_rcp_f32_e32 v1, v1
	v_rcp_f32_e32 v24, v24
	v_med3_f32 v12, v12, s81, v176
	v_max_f32_e32 v13, v13, v13
	v_mul_f32_e32 v12, 0xbfb8aa3b, v12
	v_med3_f32 v13, v13, s81, v176
	v_lshl_add_u64 v[2:3], v[2:3], 0, s[20:21]
	v_cvt_pk_bf16_f32 v29, v33, v34
	v_cvt_pk_bf16_f32 v30, v35, v31
	v_cvt_pk_bf16_f32 v31, v36, v37
	v_rcp_f32_e32 v23, v20
	v_add_f32_e32 v20, 1.0, v21
	v_exp_f32_e32 v12, v12
	v_mul_f32_e32 v13, 0xbfb8aa3b, v13
	flat_store_dwordx4 v[2:3], v[28:31]
	v_med3_f32 v25, v25, s81, v176
	v_med3_f32 v26, v26, s81, v176
	v_rcp_f32_e32 v28, v20
	v_add_f32_e32 v20, 1.0, v22
	v_exp_f32_e32 v13, v13
	v_mul_f32_e32 v25, 0xbfb8aa3b, v25
	v_mul_f32_e32 v26, 0xbfb8aa3b, v26
	v_rcp_f32_e32 v29, v20
	v_cvt_pk_bf16_f32 v20, v1, v24
	v_max_f32_e32 v1, v16, v16
	v_max_f32_e32 v16, v17, v17
	v_exp_f32_e32 v25, v25
	v_exp_f32_e32 v26, v26
	v_med3_f32 v1, v1, s81, v176
	v_med3_f32 v16, v16, s81, v176
	v_mul_f32_e32 v1, 0xbfb8aa3b, v1
	v_mul_f32_e32 v16, 0xbfb8aa3b, v16
	v_add_f32_e32 v12, 1.0, v12
	v_exp_f32_e32 v1, v1
	v_exp_f32_e32 v16, v16
	v_max_f32_e32 v17, v18, v18
	v_max_f32_e32 v18, v19, v19
	v_rcp_f32_e32 v19, v12
	v_add_f32_e32 v12, 1.0, v13
	v_max_f32_e32 v13, v14, v14
	v_med3_f32 v13, v13, s81, v176
	v_max_f32_e32 v14, v15, v15
	v_add_f32_e32 v25, 1.0, v25
	v_add_f32_e32 v26, 1.0, v26
	v_mul_f32_e32 v13, 0xbfb8aa3b, v13
	v_med3_f32 v14, v14, s81, v176
	v_rcp_f32_e32 v25, v25
	v_rcp_f32_e32 v26, v26
	v_exp_f32_e32 v13, v13
	v_mul_f32_e32 v14, 0xbfb8aa3b, v14
	v_add_f32_e32 v1, 1.0, v1
	v_add_f32_e32 v16, 1.0, v16
	v_exp_f32_e32 v14, v14
	v_rcp_f32_e32 v1, v1
	v_rcp_f32_e32 v16, v16
	v_cvt_pk_bf16_f32 v21, v25, v26
	v_cvt_pk_bf16_f32 v22, v27, v23
	v_cvt_pk_bf16_f32 v23, v28, v29
	v_rcp_f32_e32 v15, v12
	v_add_f32_e32 v12, 1.0, v13
	flat_store_dwordx4 v[2:3], v[20:23] offset:1024
	v_max_f32_e32 v4, v4, v4
	v_max_f32_e32 v5, v5, v5
	v_rcp_f32_e32 v20, v12
	v_add_f32_e32 v12, 1.0, v14
	v_rcp_f32_e32 v21, v12
	v_cvt_pk_bf16_f32 v12, v1, v16
	v_max_f32_e32 v1, v8, v8
	v_max_f32_e32 v8, v9, v9
	v_max_f32_e32 v9, v10, v10
	v_max_f32_e32 v10, v11, v11
	v_max_f32_e32 v6, v6, v6
	v_med3_f32 v17, v17, s81, v176
	v_med3_f32 v18, v18, s81, v176
	v_med3_f32 v1, v1, s81, v176
	v_med3_f32 v8, v8, s81, v176
	v_med3_f32 v9, v9, s81, v176
	v_med3_f32 v10, v10, s81, v176
	v_med3_f32 v4, v4, s81, v176
	v_med3_f32 v5, v5, s81, v176
	v_med3_f32 v6, v6, s81, v176
	v_max_f32_e32 v7, v7, v7
	v_mul_f32_e32 v17, 0xbfb8aa3b, v17
	v_mul_f32_e32 v18, 0xbfb8aa3b, v18
	v_mul_f32_e32 v1, 0xbfb8aa3b, v1
	v_mul_f32_e32 v8, 0xbfb8aa3b, v8
	v_mul_f32_e32 v9, 0xbfb8aa3b, v9
	v_mul_f32_e32 v10, 0xbfb8aa3b, v10
	v_mul_f32_e32 v4, 0xbfb8aa3b, v4
	v_mul_f32_e32 v5, 0xbfb8aa3b, v5
	v_mul_f32_e32 v6, 0xbfb8aa3b, v6
	v_med3_f32 v7, v7, s81, v176
	v_exp_f32_e32 v17, v17
	v_exp_f32_e32 v18, v18
	v_exp_f32_e32 v1, v1
	v_exp_f32_e32 v8, v8
	v_exp_f32_e32 v9, v9
	v_exp_f32_e32 v10, v10
	v_exp_f32_e32 v4, v4
	v_exp_f32_e32 v5, v5
	v_exp_f32_e32 v6, v6
	v_mul_f32_e32 v7, 0xbfb8aa3b, v7
	v_exp_f32_e32 v7, v7
	v_add_f32_e32 v17, 1.0, v17
	v_add_f32_e32 v18, 1.0, v18
	v_add_f32_e32 v1, 1.0, v1
	v_add_f32_e32 v8, 1.0, v8
	v_add_f32_e32 v9, 1.0, v9
	v_add_f32_e32 v10, 1.0, v10
	v_add_f32_e32 v4, 1.0, v4
	v_add_f32_e32 v5, 1.0, v5
	v_add_f32_e32 v6, 1.0, v6
	v_rcp_f32_e32 v17, v17
	v_rcp_f32_e32 v18, v18
	v_rcp_f32_e32 v1, v1
	v_rcp_f32_e32 v8, v8
	v_rcp_f32_e32 v9, v9
	v_rcp_f32_e32 v10, v10
	v_rcp_f32_e32 v4, v4
	v_rcp_f32_e32 v5, v5
	v_rcp_f32_e32 v136, v6
	v_add_f32_e32 v6, 1.0, v7
	v_rcp_f32_e32 v137, v6
	v_lshl_add_u64 v[2:3], v[2:3], 0, s[20:21]
	v_cvt_pk_bf16_f32 v13, v17, v18
	v_cvt_pk_bf16_f32 v14, v19, v15
	v_cvt_pk_bf16_f32 v15, v20, v21
	v_cvt_pk_bf16_f32 v132, v1, v8
	v_cvt_pk_bf16_f32 v133, v9, v10
	v_cvt_pk_bf16_f32 v134, v4, v5
	flat_store_dwordx4 v[2:3], v[12:15]
	s_mov_b64 s[100:101], 0x300
	v_lshl_add_u64 v[2:3], v[2:3], 0, s[100:101]

	.amdhsa_kernel _Z14fwd_megakernel4Args
		.amdhsa_group_segment_fixed_size 0
		.amdhsa_private_segment_fixed_size 0
		.amdhsa_kernarg_size 872
		.amdhsa_user_sgpr_count 2
		.amdhsa_user_sgpr_dispatch_ptr 0
		.amdhsa_user_sgpr_queue_ptr 0
		.amdhsa_user_sgpr_kernarg_segment_ptr 1
		.amdhsa_user_sgpr_dispatch_id 0
		.amdhsa_user_sgpr_kernarg_preload_length 0
		.amdhsa_user_sgpr_kernarg_preload_offset 0
		.amdhsa_user_sgpr_private_segment_size 0
		.amdhsa_uses_dynamic_stack 0
		.amdhsa_enable_private_segment 0
		.amdhsa_system_sgpr_workgroup_id_x 1
		.amdhsa_system_sgpr_workgroup_id_y 0
		.amdhsa_system_sgpr_workgroup_id_z 0
		.amdhsa_system_sgpr_workgroup_info 0
		.amdhsa_system_vgpr_workitem_id 2
		.amdhsa_next_free_vgpr 256
		.amdhsa_next_free_sgpr 102
		.amdhsa_accum_offset 256
		.amdhsa_reserve_vcc 1
		.amdhsa_float_round_mode_32 0
		.amdhsa_float_round_mode_16_64 0
		.amdhsa_float_denorm_mode_32 3
		.amdhsa_float_denorm_mode_16_64 3
		.amdhsa_dx10_clamp 1
		.amdhsa_ieee_mode 1
		.amdhsa_fp16_overflow 0
		.amdhsa_tg_split 0
		.amdhsa_exception_fp_ieee_invalid_op 0
		.amdhsa_exception_fp_denorm_src 0
		.amdhsa_exception_fp_ieee_div_zero 0
		.amdhsa_exception_fp_ieee_overflow 0
		.amdhsa_exception_fp_ieee_underflow 0
		.amdhsa_exception_fp_ieee_inexact 0
		.amdhsa_exception_int_div_zero 0
	.end_amdhsa_kernel

amdhsa.kernels:
  - .agpr_count:     0
    .args:
      - .offset:         0
        .size:           616
        .value_kind:     by_value
      - .offset:         616
        .size:           4
        .value_kind:     hidden_block_count_x
      - .offset:         620
        .size:           4
        .value_kind:     hidden_block_count_y
      - .offset:         624
        .size:           4
        .value_kind:     hidden_block_count_z
      - .offset:         628
        .size:           2
        .value_kind:     hidden_group_size_x
      - .offset:         630
        .size:           2
        .value_kind:     hidden_group_size_y
      - .offset:         632
        .size:           2
        .value_kind:     hidden_group_size_z
      - .offset:         634
        .size:           2
        .value_kind:     hidden_remainder_x
      - .offset:         636
        .size:           2
        .value_kind:     hidden_remainder_y
      - .offset:         638
        .size:           2
        .value_kind:     hidden_remainder_z
      - .offset:         656
        .size:           8
        .value_kind:     hidden_global_offset_x
      - .offset:         664
        .size:           8
        .value_kind:     hidden_global_offset_y
      - .offset:         672
        .size:           8
        .value_kind:     hidden_global_offset_z
      - .offset:         680
        .size:           2
        .value_kind:     hidden_grid_dims
      - .offset:         704
        .size:           8
        .value_kind:     hidden_multigrid_sync_arg
      - .offset:         736
        .size:           4
        .value_kind:     hidden_dynamic_lds_size
    .group_segment_fixed_size: 0
    .kernarg_segment_align: 8
    .kernarg_segment_size: 872
    .language:       OpenCL C
    .language_version:
      - 2
      - 0
    .max_flat_workgroup_size: 512
    .name:           _Z14fwd_megakernel4Args
    .private_segment_fixed_size: 0
    .sgpr_count:     108
    .sgpr_spill_count: 3
    .symbol:         _Z14fwd_megakernel4Args.kd
    .uniform_work_group_size: 1
    .uses_dynamic_stack: false
    .vgpr_count:     256
    .vgpr_spill_count: 0
    .wavefront_size: 64
